# P0 weight transposition: all 32 loads of an item in flight (was 8, one path fully serialised)
# speedup vs baseline: 1.0123x; 1.0123x over previous
.LBB0_39:
	v_lshl_add_u64 v[104:105], v[40:41], 0, s[6:7]
	v_lshl_add_u64 v[106:107], v[38:39], 0, s[6:7]
	v_lshl_add_u64 v[108:109], v[36:37], 0, s[6:7]
	v_lshl_add_u64 v[110:111], v[34:35], 0, s[6:7]
	v_lshl_add_u64 v[112:113], v[32:33], 0, s[6:7]
	v_lshl_add_u64 v[114:115], v[30:31], 0, s[6:7]
	v_lshl_add_u64 v[116:117], v[28:29], 0, s[6:7]
	v_lshl_add_u64 v[118:119], v[26:27], 0, s[6:7]
	global_load_dword v120, v[104:105], off nt
	global_load_dword v121, v[106:107], off nt
	global_load_dword v122, v[108:109], off nt
	global_load_dword v123, v[110:111], off nt
	global_load_dword v124, v[112:113], off nt
	global_load_dword v125, v[114:115], off nt
	global_load_dword v126, v[116:117], off nt
	global_load_dword v127, v[118:119], off nt
	s_add_u32 s6, s6, 0x30400
	s_addc_u32 s7, s7, 0
	v_lshl_add_u64 v[104:105], v[40:41], 0, s[6:7]
	v_lshl_add_u64 v[106:107], v[38:39], 0, s[6:7]
	v_lshl_add_u64 v[108:109], v[36:37], 0, s[6:7]
	v_lshl_add_u64 v[110:111], v[34:35], 0, s[6:7]
	v_lshl_add_u64 v[112:113], v[32:33], 0, s[6:7]
	v_lshl_add_u64 v[114:115], v[30:31], 0, s[6:7]
	v_lshl_add_u64 v[116:117], v[28:29], 0, s[6:7]
	v_lshl_add_u64 v[118:119], v[26:27], 0, s[6:7]
	global_load_dword v128, v[104:105], off nt
	global_load_dword v129, v[106:107], off nt
	global_load_dword v130, v[108:109], off nt
	global_load_dword v131, v[110:111], off nt
	global_load_dword v132, v[112:113], off nt
	global_load_dword v133, v[114:115], off nt
	global_load_dword v134, v[116:117], off nt
	global_load_dword v135, v[118:119], off nt
	s_add_u32 s6, s6, 0x30400
	s_addc_u32 s7, s7, 0
	v_lshl_add_u64 v[104:105], v[40:41], 0, s[6:7]
	v_lshl_add_u64 v[106:107], v[38:39], 0, s[6:7]
	v_lshl_add_u64 v[108:109], v[36:37], 0, s[6:7]
	v_lshl_add_u64 v[110:111], v[34:35], 0, s[6:7]
	v_lshl_add_u64 v[112:113], v[32:33], 0, s[6:7]
	v_lshl_add_u64 v[114:115], v[30:31], 0, s[6:7]
	v_lshl_add_u64 v[116:117], v[28:29], 0, s[6:7]
	v_lshl_add_u64 v[118:119], v[26:27], 0, s[6:7]
	global_load_dword v136, v[104:105], off nt
	global_load_dword v137, v[106:107], off nt
	global_load_dword v138, v[108:109], off nt
	global_load_dword v139, v[110:111], off nt
	global_load_dword v140, v[112:113], off nt
	global_load_dword v141, v[114:115], off nt
	global_load_dword v142, v[116:117], off nt
	global_load_dword v143, v[118:119], off nt
	s_add_u32 s6, s6, 0x30400
	s_addc_u32 s7, s7, 0
	v_lshl_add_u64 v[104:105], v[40:41], 0, s[6:7]
	v_lshl_add_u64 v[106:107], v[38:39], 0, s[6:7]
	v_lshl_add_u64 v[108:109], v[36:37], 0, s[6:7]
	v_lshl_add_u64 v[110:111], v[34:35], 0, s[6:7]
	v_lshl_add_u64 v[112:113], v[32:33], 0, s[6:7]
	v_lshl_add_u64 v[114:115], v[30:31], 0, s[6:7]
	v_lshl_add_u64 v[116:117], v[28:29], 0, s[6:7]
	v_lshl_add_u64 v[118:119], v[26:27], 0, s[6:7]
	global_load_dword v144, v[104:105], off nt
	global_load_dword v145, v[106:107], off nt
	global_load_dword v146, v[108:109], off nt
	global_load_dword v147, v[110:111], off nt
	global_load_dword v148, v[112:113], off nt
	global_load_dword v149, v[114:115], off nt
	global_load_dword v150, v[116:117], off nt
	global_load_dword v151, v[118:119], off nt
	s_add_u32 s6, s6, 0x30400
	s_addc_u32 s7, s7, 0
	v_add_u32_e32 v185, 0x400, v0
	s_waitcnt vmcnt(30)
	ds_write2_b32 v0, v120, v121 offset1:66
	s_waitcnt vmcnt(28)
	ds_write2_b32 v0, v122, v123 offset0:132 offset1:198
	s_waitcnt vmcnt(26)
	ds_write2_b32 v185, v124, v125 offset0:8 offset1:74
	s_waitcnt vmcnt(24)
	ds_write2_b32 v185, v126, v127 offset0:140 offset1:206
	v_add_u32_e32 v184, 0x840, v0
	v_add_u32_e32 v185, 0xc40, v0
	s_waitcnt vmcnt(22)
	ds_write2_b32 v184, v128, v129 offset1:66
	s_waitcnt vmcnt(20)
	ds_write2_b32 v184, v130, v131 offset0:132 offset1:198
	s_waitcnt vmcnt(18)
	ds_write2_b32 v185, v132, v133 offset0:8 offset1:74
	s_waitcnt vmcnt(16)
	ds_write2_b32 v185, v134, v135 offset0:140 offset1:206
	v_add_u32_e32 v184, 0x1080, v0
	v_add_u32_e32 v185, 0x1480, v0
	s_waitcnt vmcnt(14)
	ds_write2_b32 v184, v136, v137 offset1:66
	s_waitcnt vmcnt(12)
	ds_write2_b32 v184, v138, v139 offset0:132 offset1:198
	s_waitcnt vmcnt(10)
	ds_write2_b32 v185, v140, v141 offset0:8 offset1:74
	s_waitcnt vmcnt(8)
	ds_write2_b32 v185, v142, v143 offset0:140 offset1:206
	v_add_u32_e32 v184, 0x18c0, v0
	v_add_u32_e32 v185, 0x1cc0, v0
	s_waitcnt vmcnt(6)
	ds_write2_b32 v184, v144, v145 offset1:66
	s_waitcnt vmcnt(4)
	ds_write2_b32 v184, v146, v147 offset0:132 offset1:198
	s_waitcnt vmcnt(2)
	ds_write2_b32 v185, v148, v149 offset0:8 offset1:74
	s_waitcnt vmcnt(0)
	ds_write2_b32 v185, v150, v151 offset0:140 offset1:206
	s_cmp_lg_u32 s6, 0xc1000
	s_waitcnt lgkmcnt(0)
	ds_read2_b32 v[30:31], v60 offset0:33 offset1:41
	ds_read2_b32 v[32:33], v60 offset1:8
	ds_read2_b32 v[34:35], v60 offset0:66 offset1:74
	ds_read2_b32 v[36:37], v60 offset0:99 offset1:107
	ds_read2_b32 v[38:39], v60 offset0:132 offset1:140
	ds_read2_b32 v[40:41], v60 offset0:165 offset1:173
	ds_read2_b32 v[42:43], v60 offset0:198 offset1:206
	ds_read2_b32 v[44:45], v60 offset0:231 offset1:239
	s_and_b32 s6, 0xffff, s21
	s_lshl_b32 s14, s6, 1
	v_or_b32_e32 v0, s20, v59
	v_lshl_add_u64 v[46:47], v[2:3], 0, s[14:15]
	v_lshlrev_b32_e32 v0, 11, v0
	v_lshl_add_u64 v[48:49], v[46:47], 0, v[0:1]
	s_waitcnt lgkmcnt(6)
	v_cvt_pk_bf16_f32 v26, v32, v30
	s_waitcnt lgkmcnt(4)
	v_cvt_pk_bf16_f32 v27, v34, v36
	s_waitcnt lgkmcnt(2)
	v_cvt_pk_bf16_f32 v28, v38, v40
	s_waitcnt lgkmcnt(0)
	v_cvt_pk_bf16_f32 v29, v42, v44
	global_store_dwordx4 v[48:49], v[26:29], off
	v_or_b32_e32 v0, s20, v61
	v_lshlrev_b32_e32 v0, 11, v0
	v_cvt_pk_bf16_f32 v26, v33, v31
	v_cvt_pk_bf16_f32 v27, v35, v37
	v_cvt_pk_bf16_f32 v28, v39, v41
	v_cvt_pk_bf16_f32 v29, v43, v45
	ds_read2_b32 v[32:33], v60 offset0:16 offset1:24
	ds_read2_b32 v[34:35], v60 offset0:49 offset1:57
	ds_read2_b32 v[36:37], v60 offset0:82 offset1:90
	ds_read2_b32 v[38:39], v60 offset0:115 offset1:123
	ds_read2_b32 v[40:41], v60 offset0:148 offset1:156
	ds_read2_b32 v[42:43], v60 offset0:181 offset1:189
	ds_read2_b32 v[44:45], v60 offset0:214 offset1:222
	ds_read2_b32 v[48:49], v60 offset0:247 offset1:255
	v_lshl_add_u64 v[30:31], v[46:47], 0, v[0:1]
	v_or_b32_e32 v0, s20, v62
	v_lshlrev_b32_e32 v0, 11, v0
	global_store_dwordx4 v[30:31], v[26:29], off
	v_lshl_add_u64 v[30:31], v[46:47], 0, v[0:1]
	v_or_b32_e32 v0, s20, v63
	v_lshlrev_b32_e32 v0, 11, v0
	s_waitcnt lgkmcnt(6)
	v_cvt_pk_bf16_f32 v26, v32, v34
	s_waitcnt lgkmcnt(4)
	v_cvt_pk_bf16_f32 v27, v36, v38
	s_waitcnt lgkmcnt(2)
	v_cvt_pk_bf16_f32 v28, v40, v42
	s_waitcnt lgkmcnt(0)
	v_cvt_pk_bf16_f32 v29, v44, v48
	global_store_dwordx4 v[30:31], v[26:29], off
	v_lshl_add_u64 v[30:31], v[46:47], 0, v[0:1]
	s_mov_b64 s[6:7], 0
	v_cvt_pk_bf16_f32 v26, v33, v35
	v_cvt_pk_bf16_f32 v27, v37, v39
	v_cvt_pk_bf16_f32 v28, v41, v43
	v_cvt_pk_bf16_f32 v29, v45, v49
	global_store_dwordx4 v[30:31], v[26:29], off
	s_waitcnt lgkmcnt(0)

.LBB0_43:
	v_lshl_add_u64 v[104:105], v[40:41], 0, s[6:7]
	v_lshl_add_u64 v[106:107], v[38:39], 0, s[6:7]
	v_lshl_add_u64 v[108:109], v[36:37], 0, s[6:7]
	v_lshl_add_u64 v[110:111], v[34:35], 0, s[6:7]
	v_lshl_add_u64 v[112:113], v[32:33], 0, s[6:7]
	v_lshl_add_u64 v[114:115], v[30:31], 0, s[6:7]
	v_lshl_add_u64 v[116:117], v[28:29], 0, s[6:7]
	v_lshl_add_u64 v[118:119], v[26:27], 0, s[6:7]
	global_load_dword v120, v[104:105], off nt
	global_load_dword v121, v[106:107], off nt
	global_load_dword v122, v[108:109], off nt
	global_load_dword v123, v[110:111], off nt
	global_load_dword v124, v[112:113], off nt
	global_load_dword v125, v[114:115], off nt
	global_load_dword v126, v[116:117], off nt
	global_load_dword v127, v[118:119], off nt
	s_add_u32 s6, s6, 0x10000
	s_addc_u32 s7, s7, 0
	v_lshl_add_u64 v[104:105], v[40:41], 0, s[6:7]
	v_lshl_add_u64 v[106:107], v[38:39], 0, s[6:7]
	v_lshl_add_u64 v[108:109], v[36:37], 0, s[6:7]
	v_lshl_add_u64 v[110:111], v[34:35], 0, s[6:7]
	v_lshl_add_u64 v[112:113], v[32:33], 0, s[6:7]
	v_lshl_add_u64 v[114:115], v[30:31], 0, s[6:7]
	v_lshl_add_u64 v[116:117], v[28:29], 0, s[6:7]
	v_lshl_add_u64 v[118:119], v[26:27], 0, s[6:7]
	global_load_dword v128, v[104:105], off nt
	global_load_dword v129, v[106:107], off nt
	global_load_dword v130, v[108:109], off nt
	global_load_dword v131, v[110:111], off nt
	global_load_dword v132, v[112:113], off nt
	global_load_dword v133, v[114:115], off nt
	global_load_dword v134, v[116:117], off nt
	global_load_dword v135, v[118:119], off nt
	s_add_u32 s6, s6, 0x10000
	s_addc_u32 s7, s7, 0
	v_lshl_add_u64 v[104:105], v[40:41], 0, s[6:7]
	v_lshl_add_u64 v[106:107], v[38:39], 0, s[6:7]
	v_lshl_add_u64 v[108:109], v[36:37], 0, s[6:7]
	v_lshl_add_u64 v[110:111], v[34:35], 0, s[6:7]
	v_lshl_add_u64 v[112:113], v[32:33], 0, s[6:7]
	v_lshl_add_u64 v[114:115], v[30:31], 0, s[6:7]
	v_lshl_add_u64 v[116:117], v[28:29], 0, s[6:7]
	v_lshl_add_u64 v[118:119], v[26:27], 0, s[6:7]
	global_load_dword v136, v[104:105], off nt
	global_load_dword v137, v[106:107], off nt
	global_load_dword v138, v[108:109], off nt
	global_load_dword v139, v[110:111], off nt
	global_load_dword v140, v[112:113], off nt
	global_load_dword v141, v[114:115], off nt
	global_load_dword v142, v[116:117], off nt
	global_load_dword v143, v[118:119], off nt
	s_add_u32 s6, s6, 0x10000
	s_addc_u32 s7, s7, 0
	v_lshl_add_u64 v[104:105], v[40:41], 0, s[6:7]
	v_lshl_add_u64 v[106:107], v[38:39], 0, s[6:7]
	v_lshl_add_u64 v[108:109], v[36:37], 0, s[6:7]
	v_lshl_add_u64 v[110:111], v[34:35], 0, s[6:7]
	v_lshl_add_u64 v[112:113], v[32:33], 0, s[6:7]
	v_lshl_add_u64 v[114:115], v[30:31], 0, s[6:7]
	v_lshl_add_u64 v[116:117], v[28:29], 0, s[6:7]
	v_lshl_add_u64 v[118:119], v[26:27], 0, s[6:7]
	global_load_dword v144, v[104:105], off nt
	global_load_dword v145, v[106:107], off nt
	global_load_dword v146, v[108:109], off nt
	global_load_dword v147, v[110:111], off nt
	global_load_dword v148, v[112:113], off nt
	global_load_dword v149, v[114:115], off nt
	global_load_dword v150, v[116:117], off nt
	global_load_dword v151, v[118:119], off nt
	s_add_u32 s6, s6, 0x10000
	s_addc_u32 s7, s7, 0
	v_add_u32_e32 v185, 0x400, v0
	s_waitcnt vmcnt(30)
	ds_write2_b32 v0, v120, v121 offset1:66
	s_waitcnt vmcnt(28)
	ds_write2_b32 v0, v122, v123 offset0:132 offset1:198
	s_waitcnt vmcnt(26)
	ds_write2_b32 v185, v124, v125 offset0:8 offset1:74
	s_waitcnt vmcnt(24)
	ds_write2_b32 v185, v126, v127 offset0:140 offset1:206
	v_add_u32_e32 v184, 0x840, v0
	v_add_u32_e32 v185, 0xc40, v0
	s_waitcnt vmcnt(22)
	ds_write2_b32 v184, v128, v129 offset1:66
	s_waitcnt vmcnt(20)
	ds_write2_b32 v184, v130, v131 offset0:132 offset1:198
	s_waitcnt vmcnt(18)
	ds_write2_b32 v185, v132, v133 offset0:8 offset1:74
	s_waitcnt vmcnt(16)
	ds_write2_b32 v185, v134, v135 offset0:140 offset1:206
	v_add_u32_e32 v184, 0x1080, v0
	v_add_u32_e32 v185, 0x1480, v0
	s_waitcnt vmcnt(14)
	ds_write2_b32 v184, v136, v137 offset1:66
	s_waitcnt vmcnt(12)
	ds_write2_b32 v184, v138, v139 offset0:132 offset1:198
	s_waitcnt vmcnt(10)
	ds_write2_b32 v185, v140, v141 offset0:8 offset1:74
	s_waitcnt vmcnt(8)
	ds_write2_b32 v185, v142, v143 offset0:140 offset1:206
	v_add_u32_e32 v184, 0x18c0, v0
	v_add_u32_e32 v185, 0x1cc0, v0
	s_waitcnt vmcnt(6)
	ds_write2_b32 v184, v144, v145 offset1:66
	s_waitcnt vmcnt(4)
	ds_write2_b32 v184, v146, v147 offset0:132 offset1:198
	s_waitcnt vmcnt(2)
	ds_write2_b32 v185, v148, v149 offset0:8 offset1:74
	s_waitcnt vmcnt(0)
	ds_write2_b32 v185, v150, v151 offset0:140 offset1:206
	s_cmp_lg_u32 s6, 0x40000
	s_waitcnt lgkmcnt(0)
	s_lshl_b32 s6, s54, 1
	s_add_i32 s6, s6, 0x1b400
	s_lshl_b32 s7, s54, 5
	ds_read2_b32 v[30:31], v60 offset0:33 offset1:41
	ds_read2_b32 v[32:33], v60 offset1:8
	ds_read2_b32 v[34:35], v60 offset0:66 offset1:74
	ds_read2_b32 v[36:37], v60 offset0:99 offset1:107
	ds_read2_b32 v[38:39], v60 offset0:132 offset1:140
	ds_read2_b32 v[40:41], v60 offset0:165 offset1:173
	ds_read2_b32 v[42:43], v60 offset0:198 offset1:206
	ds_read2_b32 v[44:45], v60 offset0:231 offset1:239
	s_and_b32 s6, s6, 0x1ffc0
	s_and_b32 s7, s7, 0x3e0
	s_lshl_b32 s14, s6, 1
	v_or_b32_e32 v0, s7, v59
	v_lshl_add_u64 v[46:47], v[4:5], 0, s[14:15]
	v_lshlrev_b32_e32 v0, 11, v0
	v_lshl_add_u64 v[48:49], v[46:47], 0, v[0:1]
	s_waitcnt lgkmcnt(6)
	v_cvt_pk_bf16_f32 v26, v32, v30
	s_waitcnt lgkmcnt(4)
	v_cvt_pk_bf16_f32 v27, v34, v36
	s_waitcnt lgkmcnt(2)
	v_cvt_pk_bf16_f32 v28, v38, v40
	s_waitcnt lgkmcnt(0)
	v_cvt_pk_bf16_f32 v29, v42, v44
	global_store_dwordx4 v[48:49], v[26:29], off
	v_or_b32_e32 v0, s7, v61
	v_lshlrev_b32_e32 v0, 11, v0
	v_cvt_pk_bf16_f32 v26, v33, v31
	v_cvt_pk_bf16_f32 v27, v35, v37
	v_cvt_pk_bf16_f32 v28, v39, v41
	v_cvt_pk_bf16_f32 v29, v43, v45
	ds_read2_b32 v[32:33], v60 offset0:16 offset1:24
	ds_read2_b32 v[34:35], v60 offset0:49 offset1:57
	ds_read2_b32 v[36:37], v60 offset0:82 offset1:90
	ds_read2_b32 v[38:39], v60 offset0:115 offset1:123
	ds_read2_b32 v[40:41], v60 offset0:148 offset1:156
	ds_read2_b32 v[42:43], v60 offset0:181 offset1:189
	ds_read2_b32 v[44:45], v60 offset0:214 offset1:222
	ds_read2_b32 v[48:49], v60 offset0:247 offset1:255
	v_lshl_add_u64 v[30:31], v[46:47], 0, v[0:1]
	v_or_b32_e32 v0, s7, v62
	v_lshlrev_b32_e32 v0, 11, v0
	global_store_dwordx4 v[30:31], v[26:29], off
	v_lshl_add_u64 v[30:31], v[46:47], 0, v[0:1]
	v_or_b32_e32 v0, s7, v63
	v_lshlrev_b32_e32 v0, 11, v0
	s_waitcnt lgkmcnt(6)
	v_cvt_pk_bf16_f32 v26, v32, v34
	s_waitcnt lgkmcnt(4)
	v_cvt_pk_bf16_f32 v27, v36, v38
	s_waitcnt lgkmcnt(2)
	v_cvt_pk_bf16_f32 v28, v40, v42
	s_waitcnt lgkmcnt(0)
	v_cvt_pk_bf16_f32 v29, v44, v48
	global_store_dwordx4 v[30:31], v[26:29], off
	v_lshl_add_u64 v[30:31], v[46:47], 0, v[0:1]
	s_nop 0
	v_cvt_pk_bf16_f32 v26, v33, v35
	v_cvt_pk_bf16_f32 v27, v37, v39
	v_cvt_pk_bf16_f32 v28, v41, v43
	v_cvt_pk_bf16_f32 v29, v45, v49
	global_store_dwordx4 v[30:31], v[26:29], off
	s_waitcnt lgkmcnt(0)

.LBB0_46:
	s_andn2_b64 vcc, exec, s[6:7]
	s_cbranch_vccnz .LBB0_66
	s_and_b32 s6, s41, 0x7f
	s_lshl_b32 s14, s6, 7
	s_bfe_u32 s6, s44, 0x90007
	s_lshl_b32 s20, s6, 6
	v_or_b32_e32 v0, s20, v65
	v_lshl_or_b32 v28, v0, 14, s14
	v_or_b32_e32 v0, s20, v66
	v_lshl_or_b32 v30, v0, 14, s14
	v_or_b32_e32 v0, s20, v67
	v_lshl_or_b32 v26, s6, 8, v22
	v_lshl_or_b32 v32, v0, 14, s14
	v_or_b32_e32 v0, s20, v68
	s_load_dwordx2 s[6:7], s[12:13], 0x90
	v_lshl_or_b32 v34, v0, 14, s14
	v_or_b32_e32 v0, s20, v69
	v_lshl_or_b32 v36, v0, 14, s14
	v_or_b32_e32 v0, s20, v70
	v_lshl_or_b32 v38, v0, 14, s14
	v_or_b32_e32 v0, s20, v71
	v_lshl_or_b32 v40, v0, 14, s14
	v_or_b32_e32 v0, s20, v58
	v_mov_b32_e32 v29, v1
	v_mov_b32_e32 v31, v1
	v_mov_b32_e32 v33, v1
	v_mov_b32_e32 v35, v1
	v_mov_b32_e32 v37, v1
	v_mov_b32_e32 v39, v1
	v_mov_b32_e32 v41, v1
	v_lshl_or_b32 v42, v0, 14, s14
	v_mov_b32_e32 v43, v1
	s_waitcnt lgkmcnt(0)
	v_lshl_add_u64 v[44:45], s[6:7], 0, v[18:19]
	v_mov_b32_e32 v27, v23
	v_lshlrev_b32_e32 v0, 2, v0
	v_lshl_add_u64 v[28:29], v[44:45], 0, v[28:29]
	v_lshl_add_u64 v[30:31], v[44:45], 0, v[30:31]
	v_lshl_add_u64 v[32:33], v[44:45], 0, v[32:33]
	v_lshl_add_u64 v[34:35], v[44:45], 0, v[34:35]
	v_lshl_add_u64 v[36:37], v[44:45], 0, v[36:37]
	v_lshl_add_u64 v[38:39], v[44:45], 0, v[38:39]
	v_lshl_add_u64 v[40:41], v[44:45], 0, v[40:41]
	v_lshl_add_u64 v[42:43], v[44:45], 0, v[42:43]
	s_mov_b64 s[20:21], 0
	s_mov_b64 s[22:23], s[10:11]
	v_mov_b32_e32 v46, v64
	v_mov_b32_e32 v152, 1.0
	v_mov_b32_e32 v153, 1.0
	v_mov_b32_e32 v154, 1.0
	v_mov_b32_e32 v155, 1.0
	v_mov_b32_e32 v156, 1.0
	v_mov_b32_e32 v157, 1.0
	v_mov_b32_e32 v158, 1.0
	v_mov_b32_e32 v159, 1.0
	v_mov_b32_e32 v160, 1.0
	v_mov_b32_e32 v161, 1.0
	v_mov_b32_e32 v162, 1.0
	v_mov_b32_e32 v163, 1.0
	v_mov_b32_e32 v164, 1.0
	v_mov_b32_e32 v165, 1.0
	v_mov_b32_e32 v166, 1.0
	v_mov_b32_e32 v167, 1.0
	v_mov_b32_e32 v168, 1.0
	v_mov_b32_e32 v169, 1.0
	v_mov_b32_e32 v170, 1.0
	v_mov_b32_e32 v171, 1.0
	v_mov_b32_e32 v172, 1.0
	v_mov_b32_e32 v173, 1.0
	v_mov_b32_e32 v174, 1.0
	v_mov_b32_e32 v175, 1.0
	v_mov_b32_e32 v176, 1.0
	v_mov_b32_e32 v177, 1.0
	v_mov_b32_e32 v178, 1.0
	v_mov_b32_e32 v179, 1.0
	v_mov_b32_e32 v180, 1.0
	v_mov_b32_e32 v181, 1.0
	v_mov_b32_e32 v182, 1.0
	v_mov_b32_e32 v183, 1.0
	s_and_b64 vcc, exec, s[16:17]
	s_cbranch_vccz .Lp0w1a_nog
	v_lshl_add_u64 v[104:105], s[22:23], 0, v[0:1]
	v_lshl_add_u64 v[106:107], s[22:23], 0, v[26:27]
	global_load_dword v152, v[104:105], off
	global_load_dword v153, v[106:107], off offset:8
	global_load_dword v154, v[106:107], off offset:16
	global_load_dword v155, v[106:107], off offset:24
	global_load_dword v156, v[106:107], off offset:32
	global_load_dword v157, v[106:107], off offset:40
	global_load_dword v158, v[106:107], off offset:48
	global_load_dword v159, v[106:107], off offset:56
	s_add_u32 s22, s22, 64
	s_addc_u32 s23, s23, 0
	v_lshl_add_u64 v[104:105], s[22:23], 0, v[0:1]
	v_lshl_add_u64 v[106:107], s[22:23], 0, v[26:27]
	global_load_dword v160, v[104:105], off
	global_load_dword v161, v[106:107], off offset:8
	global_load_dword v162, v[106:107], off offset:16
	global_load_dword v163, v[106:107], off offset:24
	global_load_dword v164, v[106:107], off offset:32
	global_load_dword v165, v[106:107], off offset:40
	global_load_dword v166, v[106:107], off offset:48
	global_load_dword v167, v[106:107], off offset:56
	s_add_u32 s22, s22, 64
	s_addc_u32 s23, s23, 0
	v_lshl_add_u64 v[104:105], s[22:23], 0, v[0:1]
	v_lshl_add_u64 v[106:107], s[22:23], 0, v[26:27]
	global_load_dword v168, v[104:105], off
	global_load_dword v169, v[106:107], off offset:8
	global_load_dword v170, v[106:107], off offset:16
	global_load_dword v171, v[106:107], off offset:24
	global_load_dword v172, v[106:107], off offset:32
	global_load_dword v173, v[106:107], off offset:40
	global_load_dword v174, v[106:107], off offset:48
	global_load_dword v175, v[106:107], off offset:56
	s_add_u32 s22, s22, 64
	s_addc_u32 s23, s23, 0
	v_lshl_add_u64 v[104:105], s[22:23], 0, v[0:1]
	v_lshl_add_u64 v[106:107], s[22:23], 0, v[26:27]
	global_load_dword v176, v[104:105], off
	global_load_dword v177, v[106:107], off offset:8
	global_load_dword v178, v[106:107], off offset:16
	global_load_dword v179, v[106:107], off offset:24
	global_load_dword v180, v[106:107], off offset:32
	global_load_dword v181, v[106:107], off offset:40
	global_load_dword v182, v[106:107], off offset:48
	global_load_dword v183, v[106:107], off offset:56
	s_add_u32 s22, s22, 64
	s_addc_u32 s23, s23, 0
	s_branch .Lp0w1a_nog_j
.Lp0w1a_nog:
	s_add_u32 s22, s22, 0x100
	s_addc_u32 s23, s23, 0
.Lp0w1a_nog_j:
	v_lshl_add_u64 v[104:105], v[42:43], 0, s[20:21]
	v_lshl_add_u64 v[106:107], v[40:41], 0, s[20:21]
	v_lshl_add_u64 v[108:109], v[38:39], 0, s[20:21]
	v_lshl_add_u64 v[110:111], v[36:37], 0, s[20:21]
	v_lshl_add_u64 v[112:113], v[34:35], 0, s[20:21]
	v_lshl_add_u64 v[114:115], v[32:33], 0, s[20:21]
	v_lshl_add_u64 v[116:117], v[30:31], 0, s[20:21]
	v_lshl_add_u64 v[118:119], v[28:29], 0, s[20:21]
	global_load_dword v120, v[104:105], off nt
	global_load_dword v121, v[106:107], off nt
	global_load_dword v122, v[108:109], off nt
	global_load_dword v123, v[110:111], off nt
	global_load_dword v124, v[112:113], off nt
	global_load_dword v125, v[114:115], off nt
	global_load_dword v126, v[116:117], off nt
	global_load_dword v127, v[118:119], off nt
	s_add_u32 s20, s20, 0x40000
	s_addc_u32 s21, s21, 0
	v_lshl_add_u64 v[104:105], v[42:43], 0, s[20:21]
	v_lshl_add_u64 v[106:107], v[40:41], 0, s[20:21]
	v_lshl_add_u64 v[108:109], v[38:39], 0, s[20:21]
	v_lshl_add_u64 v[110:111], v[36:37], 0, s[20:21]
	v_lshl_add_u64 v[112:113], v[34:35], 0, s[20:21]
	v_lshl_add_u64 v[114:115], v[32:33], 0, s[20:21]
	v_lshl_add_u64 v[116:117], v[30:31], 0, s[20:21]
	v_lshl_add_u64 v[118:119], v[28:29], 0, s[20:21]
	global_load_dword v128, v[104:105], off nt
	global_load_dword v129, v[106:107], off nt
	global_load_dword v130, v[108:109], off nt
	global_load_dword v131, v[110:111], off nt
	global_load_dword v132, v[112:113], off nt
	global_load_dword v133, v[114:115], off nt
	global_load_dword v134, v[116:117], off nt
	global_load_dword v135, v[118:119], off nt
	s_add_u32 s20, s20, 0x40000
	s_addc_u32 s21, s21, 0
	v_lshl_add_u64 v[104:105], v[42:43], 0, s[20:21]
	v_lshl_add_u64 v[106:107], v[40:41], 0, s[20:21]
	v_lshl_add_u64 v[108:109], v[38:39], 0, s[20:21]
	v_lshl_add_u64 v[110:111], v[36:37], 0, s[20:21]
	v_lshl_add_u64 v[112:113], v[34:35], 0, s[20:21]
	v_lshl_add_u64 v[114:115], v[32:33], 0, s[20:21]
	v_lshl_add_u64 v[116:117], v[30:31], 0, s[20:21]
	v_lshl_add_u64 v[118:119], v[28:29], 0, s[20:21]
	global_load_dword v136, v[104:105], off nt
	global_load_dword v137, v[106:107], off nt
	global_load_dword v138, v[108:109], off nt
	global_load_dword v139, v[110:111], off nt
	global_load_dword v140, v[112:113], off nt
	global_load_dword v141, v[114:115], off nt
	global_load_dword v142, v[116:117], off nt
	global_load_dword v143, v[118:119], off nt
	s_add_u32 s20, s20, 0x40000
	s_addc_u32 s21, s21, 0
	v_lshl_add_u64 v[104:105], v[42:43], 0, s[20:21]
	v_lshl_add_u64 v[106:107], v[40:41], 0, s[20:21]
	v_lshl_add_u64 v[108:109], v[38:39], 0, s[20:21]
	v_lshl_add_u64 v[110:111], v[36:37], 0, s[20:21]
	v_lshl_add_u64 v[112:113], v[34:35], 0, s[20:21]
	v_lshl_add_u64 v[114:115], v[32:33], 0, s[20:21]
	v_lshl_add_u64 v[116:117], v[30:31], 0, s[20:21]
	v_lshl_add_u64 v[118:119], v[28:29], 0, s[20:21]
	global_load_dword v144, v[104:105], off nt
	global_load_dword v145, v[106:107], off nt
	global_load_dword v146, v[108:109], off nt
	global_load_dword v147, v[110:111], off nt
	global_load_dword v148, v[112:113], off nt
	global_load_dword v149, v[114:115], off nt
	global_load_dword v150, v[116:117], off nt
	global_load_dword v151, v[118:119], off nt
	s_add_u32 s20, s20, 0x40000
	s_addc_u32 s21, s21, 0
	v_add_u32_e32 v185, 0x400, v46
	s_waitcnt vmcnt(30)
	v_mul_f32_e32 v152, v152, v120
	v_mul_f32_e32 v153, v153, v121
	ds_write2_b32 v46, v152, v153 offset1:66
	s_waitcnt vmcnt(28)
	v_mul_f32_e32 v154, v154, v122
	v_mul_f32_e32 v155, v155, v123
	ds_write2_b32 v46, v154, v155 offset0:132 offset1:198
	s_waitcnt vmcnt(26)
	v_mul_f32_e32 v156, v156, v124
	v_mul_f32_e32 v157, v157, v125
	ds_write2_b32 v185, v156, v157 offset0:8 offset1:74
	s_waitcnt vmcnt(24)
	v_mul_f32_e32 v158, v158, v126
	v_mul_f32_e32 v159, v159, v127
	ds_write2_b32 v185, v158, v159 offset0:140 offset1:206
	v_add_u32_e32 v184, 0x840, v46
	v_add_u32_e32 v185, 0xc40, v46
	s_waitcnt vmcnt(22)
	v_mul_f32_e32 v160, v160, v128
	v_mul_f32_e32 v161, v161, v129
	ds_write2_b32 v184, v160, v161 offset1:66
	s_waitcnt vmcnt(20)
	v_mul_f32_e32 v162, v162, v130
	v_mul_f32_e32 v163, v163, v131
	ds_write2_b32 v184, v162, v163 offset0:132 offset1:198
	s_waitcnt vmcnt(18)
	v_mul_f32_e32 v164, v164, v132
	v_mul_f32_e32 v165, v165, v133
	ds_write2_b32 v185, v164, v165 offset0:8 offset1:74
	s_waitcnt vmcnt(16)
	v_mul_f32_e32 v166, v166, v134
	v_mul_f32_e32 v167, v167, v135
	ds_write2_b32 v185, v166, v167 offset0:140 offset1:206
	v_add_u32_e32 v184, 0x1080, v46
	v_add_u32_e32 v185, 0x1480, v46
	s_waitcnt vmcnt(14)
	v_mul_f32_e32 v168, v168, v136
	v_mul_f32_e32 v169, v169, v137
	ds_write2_b32 v184, v168, v169 offset1:66
	s_waitcnt vmcnt(12)
	v_mul_f32_e32 v170, v170, v138
	v_mul_f32_e32 v171, v171, v139
	ds_write2_b32 v184, v170, v171 offset0:132 offset1:198
	s_waitcnt vmcnt(10)
	v_mul_f32_e32 v172, v172, v140
	v_mul_f32_e32 v173, v173, v141
	ds_write2_b32 v185, v172, v173 offset0:8 offset1:74
	s_waitcnt vmcnt(8)
	v_mul_f32_e32 v174, v174, v142
	v_mul_f32_e32 v175, v175, v143
	ds_write2_b32 v185, v174, v175 offset0:140 offset1:206
	v_add_u32_e32 v184, 0x18c0, v46
	v_add_u32_e32 v185, 0x1cc0, v46
	s_waitcnt vmcnt(6)
	v_mul_f32_e32 v176, v176, v144
	v_mul_f32_e32 v177, v177, v145
	ds_write2_b32 v184, v176, v177 offset1:66
	s_waitcnt vmcnt(4)
	v_mul_f32_e32 v178, v178, v146
	v_mul_f32_e32 v179, v179, v147
	ds_write2_b32 v184, v178, v179 offset0:132 offset1:198
	s_waitcnt vmcnt(2)
	v_mul_f32_e32 v180, v180, v148
	v_mul_f32_e32 v181, v181, v149
	ds_write2_b32 v185, v180, v181 offset0:8 offset1:74
	s_waitcnt vmcnt(0)
	v_mul_f32_e32 v182, v182, v150
	v_mul_f32_e32 v183, v183, v151
	ds_write2_b32 v185, v182, v183 offset0:140 offset1:206
	s_cmp_lg_u32 s20, 0x100000

.LBB0_69:
	v_lshl_add_u64 v[104:105], v[40:41], 0, s[6:7]
	v_lshl_add_u64 v[106:107], v[38:39], 0, s[6:7]
	v_lshl_add_u64 v[108:109], v[36:37], 0, s[6:7]
	v_lshl_add_u64 v[110:111], v[34:35], 0, s[6:7]
	v_lshl_add_u64 v[112:113], v[32:33], 0, s[6:7]
	v_lshl_add_u64 v[114:115], v[30:31], 0, s[6:7]
	v_lshl_add_u64 v[116:117], v[28:29], 0, s[6:7]
	v_lshl_add_u64 v[118:119], v[26:27], 0, s[6:7]
	global_load_dword v120, v[104:105], off nt
	global_load_dword v121, v[106:107], off nt
	global_load_dword v122, v[108:109], off nt
	global_load_dword v123, v[110:111], off nt
	global_load_dword v124, v[112:113], off nt
	global_load_dword v125, v[114:115], off nt
	global_load_dword v126, v[116:117], off nt
	global_load_dword v127, v[118:119], off nt
	s_add_u32 s6, s6, 0x10000
	s_addc_u32 s7, s7, 0
	v_lshl_add_u64 v[104:105], v[40:41], 0, s[6:7]
	v_lshl_add_u64 v[106:107], v[38:39], 0, s[6:7]
	v_lshl_add_u64 v[108:109], v[36:37], 0, s[6:7]
	v_lshl_add_u64 v[110:111], v[34:35], 0, s[6:7]
	v_lshl_add_u64 v[112:113], v[32:33], 0, s[6:7]
	v_lshl_add_u64 v[114:115], v[30:31], 0, s[6:7]
	v_lshl_add_u64 v[116:117], v[28:29], 0, s[6:7]
	v_lshl_add_u64 v[118:119], v[26:27], 0, s[6:7]
	global_load_dword v128, v[104:105], off nt
	global_load_dword v129, v[106:107], off nt
	global_load_dword v130, v[108:109], off nt
	global_load_dword v131, v[110:111], off nt
	global_load_dword v132, v[112:113], off nt
	global_load_dword v133, v[114:115], off nt
	global_load_dword v134, v[116:117], off nt
	global_load_dword v135, v[118:119], off nt
	s_add_u32 s6, s6, 0x10000
	s_addc_u32 s7, s7, 0
	v_lshl_add_u64 v[104:105], v[40:41], 0, s[6:7]
	v_lshl_add_u64 v[106:107], v[38:39], 0, s[6:7]
	v_lshl_add_u64 v[108:109], v[36:37], 0, s[6:7]
	v_lshl_add_u64 v[110:111], v[34:35], 0, s[6:7]
	v_lshl_add_u64 v[112:113], v[32:33], 0, s[6:7]
	v_lshl_add_u64 v[114:115], v[30:31], 0, s[6:7]
	v_lshl_add_u64 v[116:117], v[28:29], 0, s[6:7]
	v_lshl_add_u64 v[118:119], v[26:27], 0, s[6:7]
	global_load_dword v136, v[104:105], off nt
	global_load_dword v137, v[106:107], off nt
	global_load_dword v138, v[108:109], off nt
	global_load_dword v139, v[110:111], off nt
	global_load_dword v140, v[112:113], off nt
	global_load_dword v141, v[114:115], off nt
	global_load_dword v142, v[116:117], off nt
	global_load_dword v143, v[118:119], off nt
	s_add_u32 s6, s6, 0x10000
	s_addc_u32 s7, s7, 0
	v_lshl_add_u64 v[104:105], v[40:41], 0, s[6:7]
	v_lshl_add_u64 v[106:107], v[38:39], 0, s[6:7]
	v_lshl_add_u64 v[108:109], v[36:37], 0, s[6:7]
	v_lshl_add_u64 v[110:111], v[34:35], 0, s[6:7]
	v_lshl_add_u64 v[112:113], v[32:33], 0, s[6:7]
	v_lshl_add_u64 v[114:115], v[30:31], 0, s[6:7]
	v_lshl_add_u64 v[116:117], v[28:29], 0, s[6:7]
	v_lshl_add_u64 v[118:119], v[26:27], 0, s[6:7]
	global_load_dword v144, v[104:105], off nt
	global_load_dword v145, v[106:107], off nt
	global_load_dword v146, v[108:109], off nt
	global_load_dword v147, v[110:111], off nt
	global_load_dword v148, v[112:113], off nt
	global_load_dword v149, v[114:115], off nt
	global_load_dword v150, v[116:117], off nt
	global_load_dword v151, v[118:119], off nt
	s_add_u32 s6, s6, 0x10000
	s_addc_u32 s7, s7, 0
	v_add_u32_e32 v185, 0x400, v0
	s_waitcnt vmcnt(30)
	ds_write2_b32 v0, v120, v121 offset1:66
	s_waitcnt vmcnt(28)
	ds_write2_b32 v0, v122, v123 offset0:132 offset1:198
	s_waitcnt vmcnt(26)
	ds_write2_b32 v185, v124, v125 offset0:8 offset1:74
	s_waitcnt vmcnt(24)
	ds_write2_b32 v185, v126, v127 offset0:140 offset1:206
	v_add_u32_e32 v184, 0x840, v0
	v_add_u32_e32 v185, 0xc40, v0
	s_waitcnt vmcnt(22)
	ds_write2_b32 v184, v128, v129 offset1:66
	s_waitcnt vmcnt(20)
	ds_write2_b32 v184, v130, v131 offset0:132 offset1:198
	s_waitcnt vmcnt(18)
	ds_write2_b32 v185, v132, v133 offset0:8 offset1:74
	s_waitcnt vmcnt(16)
	ds_write2_b32 v185, v134, v135 offset0:140 offset1:206
	v_add_u32_e32 v184, 0x1080, v0
	v_add_u32_e32 v185, 0x1480, v0
	s_waitcnt vmcnt(14)
	ds_write2_b32 v184, v136, v137 offset1:66
	s_waitcnt vmcnt(12)
	ds_write2_b32 v184, v138, v139 offset0:132 offset1:198
	s_waitcnt vmcnt(10)
	ds_write2_b32 v185, v140, v141 offset0:8 offset1:74
	s_waitcnt vmcnt(8)
	ds_write2_b32 v185, v142, v143 offset0:140 offset1:206
	v_add_u32_e32 v184, 0x18c0, v0
	v_add_u32_e32 v185, 0x1cc0, v0
	s_waitcnt vmcnt(6)
	ds_write2_b32 v184, v144, v145 offset1:66
	s_waitcnt vmcnt(4)
	ds_write2_b32 v184, v146, v147 offset0:132 offset1:198
	s_waitcnt vmcnt(2)
	ds_write2_b32 v185, v148, v149 offset0:8 offset1:74
	s_waitcnt vmcnt(0)
	ds_write2_b32 v185, v150, v151 offset0:140 offset1:206
	s_cmp_lg_u32 s6, 0x40000
	s_waitcnt lgkmcnt(0)
	s_lshl_b32 s6, s54, 1
	s_add_i32 s6, s6, 0x1d400
	s_lshl_b32 s7, s54, 5
	ds_read2_b32 v[30:31], v60 offset0:33 offset1:41
	ds_read2_b32 v[32:33], v60 offset1:8
	ds_read2_b32 v[34:35], v60 offset0:66 offset1:74
	ds_read2_b32 v[36:37], v60 offset0:99 offset1:107
	ds_read2_b32 v[38:39], v60 offset0:132 offset1:140
	ds_read2_b32 v[40:41], v60 offset0:165 offset1:173
	ds_read2_b32 v[42:43], v60 offset0:198 offset1:206
	ds_read2_b32 v[44:45], v60 offset0:231 offset1:239
	s_and_b32 s6, s6, 0x1ffc0
	s_and_b32 s7, s7, 0x3e0
	s_lshl_b32 s14, s6, 1
	v_or_b32_e32 v0, s7, v59
	v_lshl_add_u64 v[46:47], v[8:9], 0, s[14:15]
	v_lshlrev_b32_e32 v0, 13, v0
	v_lshl_add_u64 v[48:49], v[46:47], 0, v[0:1]
	s_waitcnt lgkmcnt(6)
	v_cvt_pk_bf16_f32 v26, v32, v30
	s_waitcnt lgkmcnt(4)
	v_cvt_pk_bf16_f32 v27, v34, v36
	s_waitcnt lgkmcnt(2)
	v_cvt_pk_bf16_f32 v28, v38, v40
	s_waitcnt lgkmcnt(0)
	v_cvt_pk_bf16_f32 v29, v42, v44
	global_store_dwordx4 v[48:49], v[26:29], off
	v_or_b32_e32 v0, s7, v61
	v_lshlrev_b32_e32 v0, 13, v0
	v_cvt_pk_bf16_f32 v26, v33, v31
	v_cvt_pk_bf16_f32 v27, v35, v37
	v_cvt_pk_bf16_f32 v28, v39, v41
	v_cvt_pk_bf16_f32 v29, v43, v45
	ds_read2_b32 v[32:33], v60 offset0:16 offset1:24
	ds_read2_b32 v[34:35], v60 offset0:49 offset1:57
	ds_read2_b32 v[36:37], v60 offset0:82 offset1:90
	ds_read2_b32 v[38:39], v60 offset0:115 offset1:123
	ds_read2_b32 v[40:41], v60 offset0:148 offset1:156
	ds_read2_b32 v[42:43], v60 offset0:181 offset1:189
	ds_read2_b32 v[44:45], v60 offset0:214 offset1:222
	ds_read2_b32 v[48:49], v60 offset0:247 offset1:255
	v_lshl_add_u64 v[30:31], v[46:47], 0, v[0:1]
	v_or_b32_e32 v0, s7, v62
	v_lshlrev_b32_e32 v0, 13, v0
	global_store_dwordx4 v[30:31], v[26:29], off
	v_lshl_add_u64 v[30:31], v[46:47], 0, v[0:1]
	v_or_b32_e32 v0, s7, v63
	v_lshlrev_b32_e32 v0, 13, v0
	s_waitcnt lgkmcnt(6)
	v_cvt_pk_bf16_f32 v26, v32, v34
	s_waitcnt lgkmcnt(4)
	v_cvt_pk_bf16_f32 v27, v36, v38
	s_waitcnt lgkmcnt(2)
	v_cvt_pk_bf16_f32 v28, v40, v42
	s_waitcnt lgkmcnt(0)
	v_cvt_pk_bf16_f32 v29, v44, v48
	global_store_dwordx4 v[30:31], v[26:29], off
	v_lshl_add_u64 v[30:31], v[46:47], 0, v[0:1]
	s_nop 0
	v_cvt_pk_bf16_f32 v26, v33, v35
	v_cvt_pk_bf16_f32 v27, v37, v39
	v_cvt_pk_bf16_f32 v28, v41, v43
	v_cvt_pk_bf16_f32 v29, v45, v49
	global_store_dwordx4 v[30:31], v[26:29], off
	s_waitcnt lgkmcnt(0)

.LBB0_74:
	v_lshl_add_u64 v[104:105], s[20:21], 0, v[38:39]
	v_lshl_add_u64 v[106:107], s[20:21], 0, v[36:37]
	v_lshl_add_u64 v[108:109], s[20:21], 0, v[34:35]
	v_lshl_add_u64 v[110:111], s[20:21], 0, v[32:33]
	v_lshl_add_u64 v[112:113], s[20:21], 0, v[30:31]
	v_lshl_add_u64 v[114:115], s[20:21], 0, v[28:29]
	v_lshl_add_u64 v[116:117], s[20:21], 0, v[26:27]
	v_lshl_add_u64 v[118:119], s[20:21], 0, v[0:1]
	global_load_dword v152, v[104:105], off
	global_load_dword v153, v[106:107], off
	global_load_dword v154, v[108:109], off
	global_load_dword v155, v[110:111], off
	global_load_dword v156, v[112:113], off
	global_load_dword v157, v[114:115], off
	global_load_dword v158, v[116:117], off
	global_load_dword v159, v[118:119], off
	s_add_u32 s20, s20, 64
	s_addc_u32 s21, s21, 0
	v_lshl_add_u64 v[104:105], s[20:21], 0, v[38:39]
	v_lshl_add_u64 v[106:107], s[20:21], 0, v[36:37]
	v_lshl_add_u64 v[108:109], s[20:21], 0, v[34:35]
	v_lshl_add_u64 v[110:111], s[20:21], 0, v[32:33]
	v_lshl_add_u64 v[112:113], s[20:21], 0, v[30:31]
	v_lshl_add_u64 v[114:115], s[20:21], 0, v[28:29]
	v_lshl_add_u64 v[116:117], s[20:21], 0, v[26:27]
	v_lshl_add_u64 v[118:119], s[20:21], 0, v[0:1]
	global_load_dword v160, v[104:105], off
	global_load_dword v161, v[106:107], off
	global_load_dword v162, v[108:109], off
	global_load_dword v163, v[110:111], off
	global_load_dword v164, v[112:113], off
	global_load_dword v165, v[114:115], off
	global_load_dword v166, v[116:117], off
	global_load_dword v167, v[118:119], off
	s_add_u32 s20, s20, 64
	s_addc_u32 s21, s21, 0
	v_lshl_add_u64 v[104:105], s[20:21], 0, v[38:39]
	v_lshl_add_u64 v[106:107], s[20:21], 0, v[36:37]
	v_lshl_add_u64 v[108:109], s[20:21], 0, v[34:35]
	v_lshl_add_u64 v[110:111], s[20:21], 0, v[32:33]
	v_lshl_add_u64 v[112:113], s[20:21], 0, v[30:31]
	v_lshl_add_u64 v[114:115], s[20:21], 0, v[28:29]
	v_lshl_add_u64 v[116:117], s[20:21], 0, v[26:27]
	v_lshl_add_u64 v[118:119], s[20:21], 0, v[0:1]
	global_load_dword v168, v[104:105], off
	global_load_dword v169, v[106:107], off
	global_load_dword v170, v[108:109], off
	global_load_dword v171, v[110:111], off
	global_load_dword v172, v[112:113], off
	global_load_dword v173, v[114:115], off
	global_load_dword v174, v[116:117], off
	global_load_dword v175, v[118:119], off
	s_add_u32 s20, s20, 64
	s_addc_u32 s21, s21, 0
	v_lshl_add_u64 v[104:105], s[20:21], 0, v[38:39]
	v_lshl_add_u64 v[106:107], s[20:21], 0, v[36:37]
	v_lshl_add_u64 v[108:109], s[20:21], 0, v[34:35]
	v_lshl_add_u64 v[110:111], s[20:21], 0, v[32:33]
	v_lshl_add_u64 v[112:113], s[20:21], 0, v[30:31]
	v_lshl_add_u64 v[114:115], s[20:21], 0, v[28:29]
	v_lshl_add_u64 v[116:117], s[20:21], 0, v[26:27]
	v_lshl_add_u64 v[118:119], s[20:21], 0, v[0:1]
	global_load_dword v176, v[104:105], off
	global_load_dword v177, v[106:107], off
	global_load_dword v178, v[108:109], off
	global_load_dword v179, v[110:111], off
	global_load_dword v180, v[112:113], off
	global_load_dword v181, v[114:115], off
	global_load_dword v182, v[116:117], off
	global_load_dword v183, v[118:119], off
	s_add_u32 s20, s20, 64
	s_addc_u32 s21, s21, 0
	v_lshl_add_u64 v[104:105], v[54:55], 0, s[6:7]
	v_lshl_add_u64 v[106:107], v[52:53], 0, s[6:7]
	v_lshl_add_u64 v[108:109], v[50:51], 0, s[6:7]
	v_lshl_add_u64 v[110:111], v[48:49], 0, s[6:7]
	v_lshl_add_u64 v[112:113], v[46:47], 0, s[6:7]
	v_lshl_add_u64 v[114:115], v[44:45], 0, s[6:7]
	v_lshl_add_u64 v[116:117], v[42:43], 0, s[6:7]
	v_lshl_add_u64 v[118:119], v[40:41], 0, s[6:7]
	global_load_dword v120, v[104:105], off nt
	global_load_dword v121, v[106:107], off nt
	global_load_dword v122, v[108:109], off nt
	global_load_dword v123, v[110:111], off nt
	global_load_dword v124, v[112:113], off nt
	global_load_dword v125, v[114:115], off nt
	global_load_dword v126, v[116:117], off nt
	global_load_dword v127, v[118:119], off nt
	s_add_u32 s6, s6, 0x10000
	s_addc_u32 s7, s7, 0
	v_lshl_add_u64 v[104:105], v[54:55], 0, s[6:7]
	v_lshl_add_u64 v[106:107], v[52:53], 0, s[6:7]
	v_lshl_add_u64 v[108:109], v[50:51], 0, s[6:7]
	v_lshl_add_u64 v[110:111], v[48:49], 0, s[6:7]
	v_lshl_add_u64 v[112:113], v[46:47], 0, s[6:7]
	v_lshl_add_u64 v[114:115], v[44:45], 0, s[6:7]
	v_lshl_add_u64 v[116:117], v[42:43], 0, s[6:7]
	v_lshl_add_u64 v[118:119], v[40:41], 0, s[6:7]
	global_load_dword v128, v[104:105], off nt
	global_load_dword v129, v[106:107], off nt
	global_load_dword v130, v[108:109], off nt
	global_load_dword v131, v[110:111], off nt
	global_load_dword v132, v[112:113], off nt
	global_load_dword v133, v[114:115], off nt
	global_load_dword v134, v[116:117], off nt
	global_load_dword v135, v[118:119], off nt
	s_add_u32 s6, s6, 0x10000
	s_addc_u32 s7, s7, 0
	v_lshl_add_u64 v[104:105], v[54:55], 0, s[6:7]
	v_lshl_add_u64 v[106:107], v[52:53], 0, s[6:7]
	v_lshl_add_u64 v[108:109], v[50:51], 0, s[6:7]
	v_lshl_add_u64 v[110:111], v[48:49], 0, s[6:7]
	v_lshl_add_u64 v[112:113], v[46:47], 0, s[6:7]
	v_lshl_add_u64 v[114:115], v[44:45], 0, s[6:7]
	v_lshl_add_u64 v[116:117], v[42:43], 0, s[6:7]
	v_lshl_add_u64 v[118:119], v[40:41], 0, s[6:7]
	global_load_dword v136, v[104:105], off nt
	global_load_dword v137, v[106:107], off nt
	global_load_dword v138, v[108:109], off nt
	global_load_dword v139, v[110:111], off nt
	global_load_dword v140, v[112:113], off nt
	global_load_dword v141, v[114:115], off nt
	global_load_dword v142, v[116:117], off nt
	global_load_dword v143, v[118:119], off nt
	s_add_u32 s6, s6, 0x10000
	s_addc_u32 s7, s7, 0
	v_lshl_add_u64 v[104:105], v[54:55], 0, s[6:7]
	v_lshl_add_u64 v[106:107], v[52:53], 0, s[6:7]
	v_lshl_add_u64 v[108:109], v[50:51], 0, s[6:7]
	v_lshl_add_u64 v[110:111], v[48:49], 0, s[6:7]
	v_lshl_add_u64 v[112:113], v[46:47], 0, s[6:7]
	v_lshl_add_u64 v[114:115], v[44:45], 0, s[6:7]
	v_lshl_add_u64 v[116:117], v[42:43], 0, s[6:7]
	v_lshl_add_u64 v[118:119], v[40:41], 0, s[6:7]
	global_load_dword v144, v[104:105], off nt
	global_load_dword v145, v[106:107], off nt
	global_load_dword v146, v[108:109], off nt
	global_load_dword v147, v[110:111], off nt
	global_load_dword v148, v[112:113], off nt
	global_load_dword v149, v[114:115], off nt
	global_load_dword v150, v[116:117], off nt
	global_load_dword v151, v[118:119], off nt
	s_add_u32 s6, s6, 0x10000
	s_addc_u32 s7, s7, 0
	v_add_u32_e32 v185, 0x400, v56
	s_waitcnt vmcnt(30)
	v_mul_f32_e32 v152, v152, v120
	v_mul_f32_e32 v153, v153, v121
	ds_write2_b32 v56, v152, v153 offset1:66
	s_waitcnt vmcnt(28)
	v_mul_f32_e32 v154, v154, v122
	v_mul_f32_e32 v155, v155, v123
	ds_write2_b32 v56, v154, v155 offset0:132 offset1:198
	s_waitcnt vmcnt(26)
	v_mul_f32_e32 v156, v156, v124
	v_mul_f32_e32 v157, v157, v125
	ds_write2_b32 v185, v156, v157 offset0:8 offset1:74
	s_waitcnt vmcnt(24)
	v_mul_f32_e32 v158, v158, v126
	v_mul_f32_e32 v159, v159, v127
	ds_write2_b32 v185, v158, v159 offset0:140 offset1:206
	v_add_u32_e32 v184, 0x840, v56
	v_add_u32_e32 v185, 0xc40, v56
	s_waitcnt vmcnt(22)
	v_mul_f32_e32 v160, v160, v128
	v_mul_f32_e32 v161, v161, v129
	ds_write2_b32 v184, v160, v161 offset1:66
	s_waitcnt vmcnt(20)
	v_mul_f32_e32 v162, v162, v130
	v_mul_f32_e32 v163, v163, v131
	ds_write2_b32 v184, v162, v163 offset0:132 offset1:198
	s_waitcnt vmcnt(18)
	v_mul_f32_e32 v164, v164, v132
	v_mul_f32_e32 v165, v165, v133
	ds_write2_b32 v185, v164, v165 offset0:8 offset1:74
	s_waitcnt vmcnt(16)
	v_mul_f32_e32 v166, v166, v134
	v_mul_f32_e32 v167, v167, v135
	ds_write2_b32 v185, v166, v167 offset0:140 offset1:206
	v_add_u32_e32 v184, 0x1080, v56
	v_add_u32_e32 v185, 0x1480, v56
	s_waitcnt vmcnt(14)
	v_mul_f32_e32 v168, v168, v136
	v_mul_f32_e32 v169, v169, v137
	ds_write2_b32 v184, v168, v169 offset1:66
	s_waitcnt vmcnt(12)
	v_mul_f32_e32 v170, v170, v138
	v_mul_f32_e32 v171, v171, v139
	ds_write2_b32 v184, v170, v171 offset0:132 offset1:198
	s_waitcnt vmcnt(10)
	v_mul_f32_e32 v172, v172, v140
	v_mul_f32_e32 v173, v173, v141
	ds_write2_b32 v185, v172, v173 offset0:8 offset1:74
	s_waitcnt vmcnt(8)
	v_mul_f32_e32 v174, v174, v142
	v_mul_f32_e32 v175, v175, v143
	ds_write2_b32 v185, v174, v175 offset0:140 offset1:206
	v_add_u32_e32 v184, 0x18c0, v56
	v_add_u32_e32 v185, 0x1cc0, v56
	s_waitcnt vmcnt(6)
	v_mul_f32_e32 v176, v176, v144
	v_mul_f32_e32 v177, v177, v145
	ds_write2_b32 v184, v176, v177 offset1:66
	s_waitcnt vmcnt(4)
	v_mul_f32_e32 v178, v178, v146
	v_mul_f32_e32 v179, v179, v147
	ds_write2_b32 v184, v178, v179 offset0:132 offset1:198
	s_waitcnt vmcnt(2)
	v_mul_f32_e32 v180, v180, v148
	v_mul_f32_e32 v181, v181, v149
	ds_write2_b32 v185, v180, v181 offset0:8 offset1:74
	s_waitcnt vmcnt(0)
	v_mul_f32_e32 v182, v182, v150
	v_mul_f32_e32 v183, v183, v151
	ds_write2_b32 v185, v182, v183 offset0:140 offset1:206
	s_cmp_lg_u32 s6, 0x40000
	s_waitcnt lgkmcnt(0)
	s_lshl_b32 s6, s54, 1
	s_add_i32 s6, s6, 0x1d800
	s_lshl_b32 s7, s54, 5
	ds_read2_b32 v[30:31], v60 offset0:33 offset1:41
	ds_read2_b32 v[32:33], v60 offset1:8
	ds_read2_b32 v[34:35], v60 offset0:66 offset1:74
	ds_read2_b32 v[36:37], v60 offset0:99 offset1:107
	ds_read2_b32 v[38:39], v60 offset0:132 offset1:140
	ds_read2_b32 v[40:41], v60 offset0:165 offset1:173
	ds_read2_b32 v[42:43], v60 offset0:198 offset1:206
	ds_read2_b32 v[44:45], v60 offset0:231 offset1:239
	s_and_b32 s6, s6, 0x1ffc0
	s_and_b32 s7, s7, 0x3e0
	s_lshl_b32 s14, s6, 1
	v_or_b32_e32 v0, s7, v59
	v_lshl_add_u64 v[46:47], v[10:11], 0, s[14:15]
	v_lshlrev_b32_e32 v0, 11, v0
	v_lshl_add_u64 v[48:49], v[46:47], 0, v[0:1]
	s_waitcnt lgkmcnt(6)
	v_cvt_pk_bf16_f32 v26, v32, v30
	s_waitcnt lgkmcnt(4)
	v_cvt_pk_bf16_f32 v27, v34, v36
	s_waitcnt lgkmcnt(2)
	v_cvt_pk_bf16_f32 v28, v38, v40
	s_waitcnt lgkmcnt(0)
	v_cvt_pk_bf16_f32 v29, v42, v44
	global_store_dwordx4 v[48:49], v[26:29], off
	v_or_b32_e32 v0, s7, v61
	v_lshlrev_b32_e32 v0, 11, v0
	v_cvt_pk_bf16_f32 v26, v33, v31
	v_cvt_pk_bf16_f32 v27, v35, v37
	v_cvt_pk_bf16_f32 v28, v39, v41
	v_cvt_pk_bf16_f32 v29, v43, v45
	ds_read2_b32 v[32:33], v60 offset0:16 offset1:24
	ds_read2_b32 v[34:35], v60 offset0:49 offset1:57
	ds_read2_b32 v[36:37], v60 offset0:82 offset1:90
	ds_read2_b32 v[38:39], v60 offset0:115 offset1:123
	ds_read2_b32 v[40:41], v60 offset0:148 offset1:156
	ds_read2_b32 v[42:43], v60 offset0:181 offset1:189
	ds_read2_b32 v[44:45], v60 offset0:214 offset1:222
	ds_read2_b32 v[48:49], v60 offset0:247 offset1:255
	v_lshl_add_u64 v[30:31], v[46:47], 0, v[0:1]
	v_or_b32_e32 v0, s7, v62
	v_lshlrev_b32_e32 v0, 11, v0
	global_store_dwordx4 v[30:31], v[26:29], off
	v_lshl_add_u64 v[30:31], v[46:47], 0, v[0:1]
	v_or_b32_e32 v0, s7, v63
	v_lshlrev_b32_e32 v0, 11, v0
	s_waitcnt lgkmcnt(6)
	v_cvt_pk_bf16_f32 v26, v32, v34
	s_waitcnt lgkmcnt(4)
	v_cvt_pk_bf16_f32 v27, v36, v38
	s_waitcnt lgkmcnt(2)
	v_cvt_pk_bf16_f32 v28, v40, v42
	s_waitcnt lgkmcnt(0)
	v_cvt_pk_bf16_f32 v29, v44, v48
	global_store_dwordx4 v[30:31], v[26:29], off
	v_lshl_add_u64 v[30:31], v[46:47], 0, v[0:1]
	s_nop 0
	v_cvt_pk_bf16_f32 v26, v33, v35
	v_cvt_pk_bf16_f32 v27, v37, v39
	v_cvt_pk_bf16_f32 v28, v41, v43
	v_cvt_pk_bf16_f32 v29, v45, v49
	global_store_dwordx4 v[30:31], v[26:29], off
	s_waitcnt lgkmcnt(0)

.LBB0_79:
	v_lshl_add_u64 v[104:105], v[40:41], 0, s[6:7]
	v_lshl_add_u64 v[106:107], v[38:39], 0, s[6:7]
	v_lshl_add_u64 v[108:109], v[36:37], 0, s[6:7]
	v_lshl_add_u64 v[110:111], v[34:35], 0, s[6:7]
	v_lshl_add_u64 v[112:113], v[32:33], 0, s[6:7]
	v_lshl_add_u64 v[114:115], v[30:31], 0, s[6:7]
	v_lshl_add_u64 v[116:117], v[28:29], 0, s[6:7]
	v_lshl_add_u64 v[118:119], v[26:27], 0, s[6:7]
	global_load_dword v120, v[104:105], off nt
	global_load_dword v121, v[106:107], off nt
	global_load_dword v122, v[108:109], off nt
	global_load_dword v123, v[110:111], off nt
	global_load_dword v124, v[112:113], off nt
	global_load_dword v125, v[114:115], off nt
	global_load_dword v126, v[116:117], off nt
	global_load_dword v127, v[118:119], off nt
	s_add_u32 s6, s6, 0x20000
	s_addc_u32 s7, s7, 0
	v_lshl_add_u64 v[104:105], v[40:41], 0, s[6:7]
	v_lshl_add_u64 v[106:107], v[38:39], 0, s[6:7]
	v_lshl_add_u64 v[108:109], v[36:37], 0, s[6:7]
	v_lshl_add_u64 v[110:111], v[34:35], 0, s[6:7]
	v_lshl_add_u64 v[112:113], v[32:33], 0, s[6:7]
	v_lshl_add_u64 v[114:115], v[30:31], 0, s[6:7]
	v_lshl_add_u64 v[116:117], v[28:29], 0, s[6:7]
	v_lshl_add_u64 v[118:119], v[26:27], 0, s[6:7]
	global_load_dword v128, v[104:105], off nt
	global_load_dword v129, v[106:107], off nt
	global_load_dword v130, v[108:109], off nt
	global_load_dword v131, v[110:111], off nt
	global_load_dword v132, v[112:113], off nt
	global_load_dword v133, v[114:115], off nt
	global_load_dword v134, v[116:117], off nt
	global_load_dword v135, v[118:119], off nt
	s_add_u32 s6, s6, 0x20000
	s_addc_u32 s7, s7, 0
	v_lshl_add_u64 v[104:105], v[40:41], 0, s[6:7]
	v_lshl_add_u64 v[106:107], v[38:39], 0, s[6:7]
	v_lshl_add_u64 v[108:109], v[36:37], 0, s[6:7]
	v_lshl_add_u64 v[110:111], v[34:35], 0, s[6:7]
	v_lshl_add_u64 v[112:113], v[32:33], 0, s[6:7]
	v_lshl_add_u64 v[114:115], v[30:31], 0, s[6:7]
	v_lshl_add_u64 v[116:117], v[28:29], 0, s[6:7]
	v_lshl_add_u64 v[118:119], v[26:27], 0, s[6:7]
	global_load_dword v136, v[104:105], off nt
	global_load_dword v137, v[106:107], off nt
	global_load_dword v138, v[108:109], off nt
	global_load_dword v139, v[110:111], off nt
	global_load_dword v140, v[112:113], off nt
	global_load_dword v141, v[114:115], off nt
	global_load_dword v142, v[116:117], off nt
	global_load_dword v143, v[118:119], off nt
	s_add_u32 s6, s6, 0x20000
	s_addc_u32 s7, s7, 0
	v_lshl_add_u64 v[104:105], v[40:41], 0, s[6:7]
	v_lshl_add_u64 v[106:107], v[38:39], 0, s[6:7]
	v_lshl_add_u64 v[108:109], v[36:37], 0, s[6:7]
	v_lshl_add_u64 v[110:111], v[34:35], 0, s[6:7]
	v_lshl_add_u64 v[112:113], v[32:33], 0, s[6:7]
	v_lshl_add_u64 v[114:115], v[30:31], 0, s[6:7]
	v_lshl_add_u64 v[116:117], v[28:29], 0, s[6:7]
	v_lshl_add_u64 v[118:119], v[26:27], 0, s[6:7]
	global_load_dword v144, v[104:105], off nt
	global_load_dword v145, v[106:107], off nt
	global_load_dword v146, v[108:109], off nt
	global_load_dword v147, v[110:111], off nt
	global_load_dword v148, v[112:113], off nt
	global_load_dword v149, v[114:115], off nt
	global_load_dword v150, v[116:117], off nt
	global_load_dword v151, v[118:119], off nt
	s_add_u32 s6, s6, 0x20000
	s_addc_u32 s7, s7, 0
	v_add_u32_e32 v185, 0x400, v0
	s_waitcnt vmcnt(30)
	ds_write2_b32 v0, v120, v121 offset1:66
	s_waitcnt vmcnt(28)
	ds_write2_b32 v0, v122, v123 offset0:132 offset1:198
	s_waitcnt vmcnt(26)
	ds_write2_b32 v185, v124, v125 offset0:8 offset1:74
	s_waitcnt vmcnt(24)
	ds_write2_b32 v185, v126, v127 offset0:140 offset1:206
	v_add_u32_e32 v184, 0x840, v0
	v_add_u32_e32 v185, 0xc40, v0
	s_waitcnt vmcnt(22)
	ds_write2_b32 v184, v128, v129 offset1:66
	s_waitcnt vmcnt(20)
	ds_write2_b32 v184, v130, v131 offset0:132 offset1:198
	s_waitcnt vmcnt(18)
	ds_write2_b32 v185, v132, v133 offset0:8 offset1:74
	s_waitcnt vmcnt(16)
	ds_write2_b32 v185, v134, v135 offset0:140 offset1:206
	v_add_u32_e32 v184, 0x1080, v0
	v_add_u32_e32 v185, 0x1480, v0
	s_waitcnt vmcnt(14)
	ds_write2_b32 v184, v136, v137 offset1:66
	s_waitcnt vmcnt(12)
	ds_write2_b32 v184, v138, v139 offset0:132 offset1:198
	s_waitcnt vmcnt(10)
	ds_write2_b32 v185, v140, v141 offset0:8 offset1:74
	s_waitcnt vmcnt(8)
	ds_write2_b32 v185, v142, v143 offset0:140 offset1:206
	v_add_u32_e32 v184, 0x18c0, v0
	v_add_u32_e32 v185, 0x1cc0, v0
	s_waitcnt vmcnt(6)
	ds_write2_b32 v184, v144, v145 offset1:66
	s_waitcnt vmcnt(4)
	ds_write2_b32 v184, v146, v147 offset0:132 offset1:198
	s_waitcnt vmcnt(2)
	ds_write2_b32 v185, v148, v149 offset0:8 offset1:74
	s_waitcnt vmcnt(0)
	ds_write2_b32 v185, v150, v151 offset0:140 offset1:206
	s_cmp_lg_u32 s6, 0x80000
	s_waitcnt lgkmcnt(0)
	s_add_i32 s6, s54, 0xf000
	s_lshl_b32 s7, s54, 5
	ds_read2_b32 v[30:31], v60 offset0:33 offset1:41
	ds_read2_b32 v[32:33], v60 offset1:8
	ds_read2_b32 v[34:35], v60 offset0:66 offset1:74
	ds_read2_b32 v[36:37], v60 offset0:99 offset1:107
	ds_read2_b32 v[38:39], v60 offset0:132 offset1:140
	ds_read2_b32 v[40:41], v60 offset0:165 offset1:173
	ds_read2_b32 v[42:43], v60 offset0:198 offset1:206
	ds_read2_b32 v[44:45], v60 offset0:231 offset1:239
	s_and_b32 s6, s6, 0xffc0
	s_and_b32 s7, s7, 0x7e0
	s_lshl_b32 s14, s6, 1
	v_or_b32_e32 v0, s7, v59
	v_lshl_add_u64 v[46:47], v[12:13], 0, s[14:15]
	v_lshlrev_b32_e32 v0, 11, v0
	v_lshl_add_u64 v[48:49], v[46:47], 0, v[0:1]
	s_waitcnt lgkmcnt(6)
	v_cvt_pk_bf16_f32 v26, v32, v30
	s_waitcnt lgkmcnt(4)
	v_cvt_pk_bf16_f32 v27, v34, v36
	s_waitcnt lgkmcnt(2)
	v_cvt_pk_bf16_f32 v28, v38, v40
	s_waitcnt lgkmcnt(0)
	v_cvt_pk_bf16_f32 v29, v42, v44
	global_store_dwordx4 v[48:49], v[26:29], off
	v_or_b32_e32 v0, s7, v61
	v_lshlrev_b32_e32 v0, 11, v0
	v_cvt_pk_bf16_f32 v26, v33, v31
	v_cvt_pk_bf16_f32 v27, v35, v37
	v_cvt_pk_bf16_f32 v28, v39, v41
	v_cvt_pk_bf16_f32 v29, v43, v45
	ds_read2_b32 v[32:33], v60 offset0:16 offset1:24
	ds_read2_b32 v[34:35], v60 offset0:49 offset1:57
	ds_read2_b32 v[36:37], v60 offset0:82 offset1:90
	ds_read2_b32 v[38:39], v60 offset0:115 offset1:123
	ds_read2_b32 v[40:41], v60 offset0:148 offset1:156
	ds_read2_b32 v[42:43], v60 offset0:181 offset1:189
	ds_read2_b32 v[44:45], v60 offset0:214 offset1:222
	ds_read2_b32 v[48:49], v60 offset0:247 offset1:255
	v_lshl_add_u64 v[30:31], v[46:47], 0, v[0:1]
	v_or_b32_e32 v0, s7, v62
	v_lshlrev_b32_e32 v0, 11, v0
	global_store_dwordx4 v[30:31], v[26:29], off
	v_lshl_add_u64 v[30:31], v[46:47], 0, v[0:1]
	v_or_b32_e32 v0, s7, v63
	v_lshlrev_b32_e32 v0, 11, v0
	s_waitcnt lgkmcnt(6)
	v_cvt_pk_bf16_f32 v26, v32, v34
	s_waitcnt lgkmcnt(4)
	v_cvt_pk_bf16_f32 v27, v36, v38
	s_waitcnt lgkmcnt(2)
	v_cvt_pk_bf16_f32 v28, v40, v42
	s_waitcnt lgkmcnt(0)
	v_cvt_pk_bf16_f32 v29, v44, v48
	global_store_dwordx4 v[30:31], v[26:29], off
	v_lshl_add_u64 v[30:31], v[46:47], 0, v[0:1]
	s_nop 0
	v_cvt_pk_bf16_f32 v26, v33, v35
	v_cvt_pk_bf16_f32 v27, v37, v39
	v_cvt_pk_bf16_f32 v28, v41, v43
	v_cvt_pk_bf16_f32 v29, v45, v49
	global_store_dwordx4 v[30:31], v[26:29], off
	s_waitcnt lgkmcnt(0)

.LBB0_84:
	v_lshl_add_u64 v[104:105], v[40:41], 0, s[6:7]
	v_lshl_add_u64 v[106:107], v[38:39], 0, s[6:7]
	v_lshl_add_u64 v[108:109], v[36:37], 0, s[6:7]
	v_lshl_add_u64 v[110:111], v[34:35], 0, s[6:7]
	v_lshl_add_u64 v[112:113], v[32:33], 0, s[6:7]
	v_lshl_add_u64 v[114:115], v[30:31], 0, s[6:7]
	v_lshl_add_u64 v[116:117], v[28:29], 0, s[6:7]
	v_lshl_add_u64 v[118:119], v[26:27], 0, s[6:7]
	global_load_dword v120, v[104:105], off nt
	global_load_dword v121, v[106:107], off nt
	global_load_dword v122, v[108:109], off nt
	global_load_dword v123, v[110:111], off nt
	global_load_dword v124, v[112:113], off nt
	global_load_dword v125, v[114:115], off nt
	global_load_dword v126, v[116:117], off nt
	global_load_dword v127, v[118:119], off nt
	s_add_u32 s6, s6, 0x10000
	s_addc_u32 s7, s7, 0
	v_lshl_add_u64 v[104:105], v[40:41], 0, s[6:7]
	v_lshl_add_u64 v[106:107], v[38:39], 0, s[6:7]
	v_lshl_add_u64 v[108:109], v[36:37], 0, s[6:7]
	v_lshl_add_u64 v[110:111], v[34:35], 0, s[6:7]
	v_lshl_add_u64 v[112:113], v[32:33], 0, s[6:7]
	v_lshl_add_u64 v[114:115], v[30:31], 0, s[6:7]
	v_lshl_add_u64 v[116:117], v[28:29], 0, s[6:7]
	v_lshl_add_u64 v[118:119], v[26:27], 0, s[6:7]
	global_load_dword v128, v[104:105], off nt
	global_load_dword v129, v[106:107], off nt
	global_load_dword v130, v[108:109], off nt
	global_load_dword v131, v[110:111], off nt
	global_load_dword v132, v[112:113], off nt
	global_load_dword v133, v[114:115], off nt
	global_load_dword v134, v[116:117], off nt
	global_load_dword v135, v[118:119], off nt
	s_add_u32 s6, s6, 0x10000
	s_addc_u32 s7, s7, 0
	v_lshl_add_u64 v[104:105], v[40:41], 0, s[6:7]
	v_lshl_add_u64 v[106:107], v[38:39], 0, s[6:7]
	v_lshl_add_u64 v[108:109], v[36:37], 0, s[6:7]
	v_lshl_add_u64 v[110:111], v[34:35], 0, s[6:7]
	v_lshl_add_u64 v[112:113], v[32:33], 0, s[6:7]
	v_lshl_add_u64 v[114:115], v[30:31], 0, s[6:7]
	v_lshl_add_u64 v[116:117], v[28:29], 0, s[6:7]
	v_lshl_add_u64 v[118:119], v[26:27], 0, s[6:7]
	global_load_dword v136, v[104:105], off nt
	global_load_dword v137, v[106:107], off nt
	global_load_dword v138, v[108:109], off nt
	global_load_dword v139, v[110:111], off nt
	global_load_dword v140, v[112:113], off nt
	global_load_dword v141, v[114:115], off nt
	global_load_dword v142, v[116:117], off nt
	global_load_dword v143, v[118:119], off nt
	s_add_u32 s6, s6, 0x10000
	s_addc_u32 s7, s7, 0
	v_lshl_add_u64 v[104:105], v[40:41], 0, s[6:7]
	v_lshl_add_u64 v[106:107], v[38:39], 0, s[6:7]
	v_lshl_add_u64 v[108:109], v[36:37], 0, s[6:7]
	v_lshl_add_u64 v[110:111], v[34:35], 0, s[6:7]
	v_lshl_add_u64 v[112:113], v[32:33], 0, s[6:7]
	v_lshl_add_u64 v[114:115], v[30:31], 0, s[6:7]
	v_lshl_add_u64 v[116:117], v[28:29], 0, s[6:7]
	v_lshl_add_u64 v[118:119], v[26:27], 0, s[6:7]
	global_load_dword v144, v[104:105], off nt
	global_load_dword v145, v[106:107], off nt
	global_load_dword v146, v[108:109], off nt
	global_load_dword v147, v[110:111], off nt
	global_load_dword v148, v[112:113], off nt
	global_load_dword v149, v[114:115], off nt
	global_load_dword v150, v[116:117], off nt
	global_load_dword v151, v[118:119], off nt
	s_add_u32 s6, s6, 0x10000
	s_addc_u32 s7, s7, 0
	v_add_u32_e32 v185, 0x400, v0
	s_waitcnt vmcnt(30)
	ds_write2_b32 v0, v120, v121 offset1:66
	s_waitcnt vmcnt(28)
	ds_write2_b32 v0, v122, v123 offset0:132 offset1:198
	s_waitcnt vmcnt(26)
	ds_write2_b32 v185, v124, v125 offset0:8 offset1:74
	s_waitcnt vmcnt(24)
	ds_write2_b32 v185, v126, v127 offset0:140 offset1:206
	v_add_u32_e32 v184, 0x840, v0
	v_add_u32_e32 v185, 0xc40, v0
	s_waitcnt vmcnt(22)
	ds_write2_b32 v184, v128, v129 offset1:66
	s_waitcnt vmcnt(20)
	ds_write2_b32 v184, v130, v131 offset0:132 offset1:198
	s_waitcnt vmcnt(18)
	ds_write2_b32 v185, v132, v133 offset0:8 offset1:74
	s_waitcnt vmcnt(16)
	ds_write2_b32 v185, v134, v135 offset0:140 offset1:206
	v_add_u32_e32 v184, 0x1080, v0
	v_add_u32_e32 v185, 0x1480, v0
	s_waitcnt vmcnt(14)
	ds_write2_b32 v184, v136, v137 offset1:66
	s_waitcnt vmcnt(12)
	ds_write2_b32 v184, v138, v139 offset0:132 offset1:198
	s_waitcnt vmcnt(10)
	ds_write2_b32 v185, v140, v141 offset0:8 offset1:74
	s_waitcnt vmcnt(8)
	ds_write2_b32 v185, v142, v143 offset0:140 offset1:206
	v_add_u32_e32 v184, 0x18c0, v0
	v_add_u32_e32 v185, 0x1cc0, v0
	s_waitcnt vmcnt(6)
	ds_write2_b32 v184, v144, v145 offset1:66
	s_waitcnt vmcnt(4)
	ds_write2_b32 v184, v146, v147 offset0:132 offset1:198
	s_waitcnt vmcnt(2)
	ds_write2_b32 v185, v148, v149 offset0:8 offset1:74
	s_waitcnt vmcnt(0)
	ds_write2_b32 v185, v150, v151 offset0:140 offset1:206
	s_cmp_lg_u32 s6, 0x40000
	s_waitcnt lgkmcnt(0)
	s_lshl_b32 s6, s54, 1
	s_add_i32 s6, s6, 0x1f000
	s_lshl_b32 s7, s54, 5
	ds_read2_b32 v[30:31], v60 offset0:33 offset1:41
	ds_read2_b32 v[32:33], v60 offset1:8
	ds_read2_b32 v[34:35], v60 offset0:66 offset1:74
	ds_read2_b32 v[36:37], v60 offset0:99 offset1:107
	ds_read2_b32 v[38:39], v60 offset0:132 offset1:140
	ds_read2_b32 v[40:41], v60 offset0:165 offset1:173
	ds_read2_b32 v[42:43], v60 offset0:198 offset1:206
	ds_read2_b32 v[44:45], v60 offset0:231 offset1:239
	s_and_b32 s6, s6, 0x1ffc0
	s_and_b32 s7, s7, 0x3e0
	s_lshl_b32 s14, s6, 1
	v_or_b32_e32 v0, s7, v59
	v_lshl_add_u64 v[46:47], v[14:15], 0, s[14:15]
	v_lshlrev_b32_e32 v0, 13, v0
	v_lshl_add_u64 v[48:49], v[46:47], 0, v[0:1]
	s_waitcnt lgkmcnt(6)
	v_cvt_pk_bf16_f32 v26, v32, v30
	s_waitcnt lgkmcnt(4)
	v_cvt_pk_bf16_f32 v27, v34, v36
	s_waitcnt lgkmcnt(2)
	v_cvt_pk_bf16_f32 v28, v38, v40
	s_waitcnt lgkmcnt(0)
	v_cvt_pk_bf16_f32 v29, v42, v44
	global_store_dwordx4 v[48:49], v[26:29], off
	v_or_b32_e32 v0, s7, v61
	v_lshlrev_b32_e32 v0, 13, v0
	v_cvt_pk_bf16_f32 v26, v33, v31
	v_cvt_pk_bf16_f32 v27, v35, v37
	v_cvt_pk_bf16_f32 v28, v39, v41
	v_cvt_pk_bf16_f32 v29, v43, v45
	ds_read2_b32 v[32:33], v60 offset0:16 offset1:24
	ds_read2_b32 v[34:35], v60 offset0:49 offset1:57
	ds_read2_b32 v[36:37], v60 offset0:82 offset1:90
	ds_read2_b32 v[38:39], v60 offset0:115 offset1:123
	ds_read2_b32 v[40:41], v60 offset0:148 offset1:156
	ds_read2_b32 v[42:43], v60 offset0:181 offset1:189
	ds_read2_b32 v[44:45], v60 offset0:214 offset1:222
	ds_read2_b32 v[48:49], v60 offset0:247 offset1:255
	v_lshl_add_u64 v[30:31], v[46:47], 0, v[0:1]
	v_or_b32_e32 v0, s7, v62
	v_lshlrev_b32_e32 v0, 13, v0
	global_store_dwordx4 v[30:31], v[26:29], off
	v_lshl_add_u64 v[30:31], v[46:47], 0, v[0:1]
	v_or_b32_e32 v0, s7, v63
	v_lshlrev_b32_e32 v0, 13, v0
	s_waitcnt lgkmcnt(6)
	v_cvt_pk_bf16_f32 v26, v32, v34
	s_waitcnt lgkmcnt(4)
	v_cvt_pk_bf16_f32 v27, v36, v38
	s_waitcnt lgkmcnt(2)
	v_cvt_pk_bf16_f32 v28, v40, v42
	s_waitcnt lgkmcnt(0)
	v_cvt_pk_bf16_f32 v29, v44, v48
	global_store_dwordx4 v[30:31], v[26:29], off
	v_lshl_add_u64 v[30:31], v[46:47], 0, v[0:1]
	s_nop 0
	v_cvt_pk_bf16_f32 v26, v33, v35
	v_cvt_pk_bf16_f32 v27, v37, v39
	v_cvt_pk_bf16_f32 v28, v41, v43
	v_cvt_pk_bf16_f32 v29, v45, v49
	global_store_dwordx4 v[30:31], v[26:29], off
	s_waitcnt lgkmcnt(0)

.LBB0_89:
	v_lshl_add_u64 v[104:105], s[40:41], 0, v[56:57]
	v_lshl_add_u64 v[106:107], s[40:41], 0, v[52:53]
	v_lshl_add_u64 v[108:109], s[40:41], 0, v[48:49]
	v_lshl_add_u64 v[110:111], s[40:41], 0, v[44:45]
	v_lshl_add_u64 v[112:113], s[40:41], 0, v[40:41]
	v_lshl_add_u64 v[114:115], s[40:41], 0, v[36:37]
	v_lshl_add_u64 v[116:117], s[40:41], 0, v[32:33]
	v_lshl_add_u64 v[118:119], s[40:41], 0, v[28:29]
	global_load_dword v152, v[104:105], off
	global_load_dword v153, v[106:107], off
	global_load_dword v154, v[108:109], off
	global_load_dword v155, v[110:111], off
	global_load_dword v156, v[112:113], off
	global_load_dword v157, v[114:115], off
	global_load_dword v158, v[116:117], off
	global_load_dword v159, v[118:119], off
	s_add_u32 s40, s40, 64
	s_addc_u32 s41, s41, 0
	v_lshl_add_u64 v[104:105], s[40:41], 0, v[56:57]
	v_lshl_add_u64 v[106:107], s[40:41], 0, v[52:53]
	v_lshl_add_u64 v[108:109], s[40:41], 0, v[48:49]
	v_lshl_add_u64 v[110:111], s[40:41], 0, v[44:45]
	v_lshl_add_u64 v[112:113], s[40:41], 0, v[40:41]
	v_lshl_add_u64 v[114:115], s[40:41], 0, v[36:37]
	v_lshl_add_u64 v[116:117], s[40:41], 0, v[32:33]
	v_lshl_add_u64 v[118:119], s[40:41], 0, v[28:29]
	global_load_dword v160, v[104:105], off
	global_load_dword v161, v[106:107], off
	global_load_dword v162, v[108:109], off
	global_load_dword v163, v[110:111], off
	global_load_dword v164, v[112:113], off
	global_load_dword v165, v[114:115], off
	global_load_dword v166, v[116:117], off
	global_load_dword v167, v[118:119], off
	s_add_u32 s40, s40, 64
	s_addc_u32 s41, s41, 0
	v_lshl_add_u64 v[104:105], s[40:41], 0, v[56:57]
	v_lshl_add_u64 v[106:107], s[40:41], 0, v[52:53]
	v_lshl_add_u64 v[108:109], s[40:41], 0, v[48:49]
	v_lshl_add_u64 v[110:111], s[40:41], 0, v[44:45]
	v_lshl_add_u64 v[112:113], s[40:41], 0, v[40:41]
	v_lshl_add_u64 v[114:115], s[40:41], 0, v[36:37]
	v_lshl_add_u64 v[116:117], s[40:41], 0, v[32:33]
	v_lshl_add_u64 v[118:119], s[40:41], 0, v[28:29]
	global_load_dword v168, v[104:105], off
	global_load_dword v169, v[106:107], off
	global_load_dword v170, v[108:109], off
	global_load_dword v171, v[110:111], off
	global_load_dword v172, v[112:113], off
	global_load_dword v173, v[114:115], off
	global_load_dword v174, v[116:117], off
	global_load_dword v175, v[118:119], off
	s_add_u32 s40, s40, 64
	s_addc_u32 s41, s41, 0
	v_lshl_add_u64 v[104:105], s[40:41], 0, v[56:57]
	v_lshl_add_u64 v[106:107], s[40:41], 0, v[52:53]
	v_lshl_add_u64 v[108:109], s[40:41], 0, v[48:49]
	v_lshl_add_u64 v[110:111], s[40:41], 0, v[44:45]
	v_lshl_add_u64 v[112:113], s[40:41], 0, v[40:41]
	v_lshl_add_u64 v[114:115], s[40:41], 0, v[36:37]
	v_lshl_add_u64 v[116:117], s[40:41], 0, v[32:33]
	v_lshl_add_u64 v[118:119], s[40:41], 0, v[28:29]
	global_load_dword v176, v[104:105], off
	global_load_dword v177, v[106:107], off
	global_load_dword v178, v[108:109], off
	global_load_dword v179, v[110:111], off
	global_load_dword v180, v[112:113], off
	global_load_dword v181, v[114:115], off
	global_load_dword v182, v[116:117], off
	global_load_dword v183, v[118:119], off
	s_add_u32 s40, s40, 64
	s_addc_u32 s41, s41, 0
	v_lshl_add_u64 v[104:105], v[54:55], 0, s[22:23]
	v_lshl_add_u64 v[106:107], v[50:51], 0, s[22:23]
	v_lshl_add_u64 v[108:109], v[46:47], 0, s[22:23]
	v_lshl_add_u64 v[110:111], v[42:43], 0, s[22:23]
	v_lshl_add_u64 v[112:113], v[38:39], 0, s[22:23]
	v_lshl_add_u64 v[114:115], v[34:35], 0, s[22:23]
	v_lshl_add_u64 v[116:117], v[30:31], 0, s[22:23]
	v_lshl_add_u64 v[118:119], v[26:27], 0, s[22:23]
	global_load_dword v120, v[104:105], off nt
	global_load_dword v121, v[106:107], off nt
	global_load_dword v122, v[108:109], off nt
	global_load_dword v123, v[110:111], off nt
	global_load_dword v124, v[112:113], off nt
	global_load_dword v125, v[114:115], off nt
	global_load_dword v126, v[116:117], off nt
	global_load_dword v127, v[118:119], off nt
	s_add_u32 s22, s22, 0x40000
	s_addc_u32 s23, s23, 0
	v_lshl_add_u64 v[104:105], v[54:55], 0, s[22:23]
	v_lshl_add_u64 v[106:107], v[50:51], 0, s[22:23]
	v_lshl_add_u64 v[108:109], v[46:47], 0, s[22:23]
	v_lshl_add_u64 v[110:111], v[42:43], 0, s[22:23]
	v_lshl_add_u64 v[112:113], v[38:39], 0, s[22:23]
	v_lshl_add_u64 v[114:115], v[34:35], 0, s[22:23]
	v_lshl_add_u64 v[116:117], v[30:31], 0, s[22:23]
	v_lshl_add_u64 v[118:119], v[26:27], 0, s[22:23]
	global_load_dword v128, v[104:105], off nt
	global_load_dword v129, v[106:107], off nt
	global_load_dword v130, v[108:109], off nt
	global_load_dword v131, v[110:111], off nt
	global_load_dword v132, v[112:113], off nt
	global_load_dword v133, v[114:115], off nt
	global_load_dword v134, v[116:117], off nt
	global_load_dword v135, v[118:119], off nt
	s_add_u32 s22, s22, 0x40000
	s_addc_u32 s23, s23, 0
	v_lshl_add_u64 v[104:105], v[54:55], 0, s[22:23]
	v_lshl_add_u64 v[106:107], v[50:51], 0, s[22:23]
	v_lshl_add_u64 v[108:109], v[46:47], 0, s[22:23]
	v_lshl_add_u64 v[110:111], v[42:43], 0, s[22:23]
	v_lshl_add_u64 v[112:113], v[38:39], 0, s[22:23]
	v_lshl_add_u64 v[114:115], v[34:35], 0, s[22:23]
	v_lshl_add_u64 v[116:117], v[30:31], 0, s[22:23]
	v_lshl_add_u64 v[118:119], v[26:27], 0, s[22:23]
	global_load_dword v136, v[104:105], off nt
	global_load_dword v137, v[106:107], off nt
	global_load_dword v138, v[108:109], off nt
	global_load_dword v139, v[110:111], off nt
	global_load_dword v140, v[112:113], off nt
	global_load_dword v141, v[114:115], off nt
	global_load_dword v142, v[116:117], off nt
	global_load_dword v143, v[118:119], off nt
	s_add_u32 s22, s22, 0x40000
	s_addc_u32 s23, s23, 0
	v_lshl_add_u64 v[104:105], v[54:55], 0, s[22:23]
	v_lshl_add_u64 v[106:107], v[50:51], 0, s[22:23]
	v_lshl_add_u64 v[108:109], v[46:47], 0, s[22:23]
	v_lshl_add_u64 v[110:111], v[42:43], 0, s[22:23]
	v_lshl_add_u64 v[112:113], v[38:39], 0, s[22:23]
	v_lshl_add_u64 v[114:115], v[34:35], 0, s[22:23]
	v_lshl_add_u64 v[116:117], v[30:31], 0, s[22:23]
	v_lshl_add_u64 v[118:119], v[26:27], 0, s[22:23]
	global_load_dword v144, v[104:105], off nt
	global_load_dword v145, v[106:107], off nt
	global_load_dword v146, v[108:109], off nt
	global_load_dword v147, v[110:111], off nt
	global_load_dword v148, v[112:113], off nt
	global_load_dword v149, v[114:115], off nt
	global_load_dword v150, v[116:117], off nt
	global_load_dword v151, v[118:119], off nt
	s_add_u32 s22, s22, 0x40000
	s_addc_u32 s23, s23, 0
	v_add_u32_e32 v185, 0x400, v0
	s_waitcnt vmcnt(30)
	v_mul_f32_e32 v152, v152, v120
	v_mul_f32_e32 v153, v153, v121
	ds_write2_b32 v0, v152, v153 offset1:66
	s_waitcnt vmcnt(28)
	v_mul_f32_e32 v154, v154, v122
	v_mul_f32_e32 v155, v155, v123
	ds_write2_b32 v0, v154, v155 offset0:132 offset1:198
	s_waitcnt vmcnt(26)
	v_mul_f32_e32 v156, v156, v124
	v_mul_f32_e32 v157, v157, v125
	ds_write2_b32 v185, v156, v157 offset0:8 offset1:74
	s_waitcnt vmcnt(24)
	v_mul_f32_e32 v158, v158, v126
	v_mul_f32_e32 v159, v159, v127
	ds_write2_b32 v185, v158, v159 offset0:140 offset1:206
	v_add_u32_e32 v184, 0x840, v0
	v_add_u32_e32 v185, 0xc40, v0
	s_waitcnt vmcnt(22)
	v_mul_f32_e32 v160, v160, v128
	v_mul_f32_e32 v161, v161, v129
	ds_write2_b32 v184, v160, v161 offset1:66
	s_waitcnt vmcnt(20)
	v_mul_f32_e32 v162, v162, v130
	v_mul_f32_e32 v163, v163, v131
	ds_write2_b32 v184, v162, v163 offset0:132 offset1:198
	s_waitcnt vmcnt(18)
	v_mul_f32_e32 v164, v164, v132
	v_mul_f32_e32 v165, v165, v133
	ds_write2_b32 v185, v164, v165 offset0:8 offset1:74
	s_waitcnt vmcnt(16)
	v_mul_f32_e32 v166, v166, v134
	v_mul_f32_e32 v167, v167, v135
	ds_write2_b32 v185, v166, v167 offset0:140 offset1:206
	v_add_u32_e32 v184, 0x1080, v0
	v_add_u32_e32 v185, 0x1480, v0
	s_waitcnt vmcnt(14)
	v_mul_f32_e32 v168, v168, v136
	v_mul_f32_e32 v169, v169, v137
	ds_write2_b32 v184, v168, v169 offset1:66
	s_waitcnt vmcnt(12)
	v_mul_f32_e32 v170, v170, v138
	v_mul_f32_e32 v171, v171, v139
	ds_write2_b32 v184, v170, v171 offset0:132 offset1:198
	s_waitcnt vmcnt(10)
	v_mul_f32_e32 v172, v172, v140
	v_mul_f32_e32 v173, v173, v141
	ds_write2_b32 v185, v172, v173 offset0:8 offset1:74
	s_waitcnt vmcnt(8)
	v_mul_f32_e32 v174, v174, v142
	v_mul_f32_e32 v175, v175, v143
	ds_write2_b32 v185, v174, v175 offset0:140 offset1:206
	v_add_u32_e32 v184, 0x18c0, v0
	v_add_u32_e32 v185, 0x1cc0, v0
	s_waitcnt vmcnt(6)
	v_mul_f32_e32 v176, v176, v144
	v_mul_f32_e32 v177, v177, v145
	ds_write2_b32 v184, v176, v177 offset1:66
	s_waitcnt vmcnt(4)
	v_mul_f32_e32 v178, v178, v146
	v_mul_f32_e32 v179, v179, v147
	ds_write2_b32 v184, v178, v179 offset0:132 offset1:198
	s_waitcnt vmcnt(2)
	v_mul_f32_e32 v180, v180, v148
	v_mul_f32_e32 v181, v181, v149
	ds_write2_b32 v185, v180, v181 offset0:8 offset1:74
	s_waitcnt vmcnt(0)
	v_mul_f32_e32 v182, v182, v150
	v_mul_f32_e32 v183, v183, v151
	ds_write2_b32 v185, v182, v183 offset0:140 offset1:206
	s_cmp_lg_u32 s22, 0x100000
	s_waitcnt lgkmcnt(0)
	ds_read2_b32 v[30:31], v60 offset0:33 offset1:41
	ds_read2_b32 v[32:33], v60 offset1:8
	ds_read2_b32 v[34:35], v60 offset0:66 offset1:74
	ds_read2_b32 v[36:37], v60 offset0:99 offset1:107
	ds_read2_b32 v[38:39], v60 offset0:132 offset1:140
	ds_read2_b32 v[40:41], v60 offset0:165 offset1:173
	ds_read2_b32 v[42:43], v60 offset0:198 offset1:206
	ds_read2_b32 v[44:45], v60 offset0:231 offset1:239
	v_or_b32_e32 v48, s6, v59
	s_ashr_i32 s21, s20, 31
	v_ashrrev_i32_e32 v49, 31, v48
	v_lshl_add_u64 v[46:47], s[20:21], 1, v[16:17]
	v_lshlrev_b64 v[48:49], 11, v[48:49]
	s_waitcnt lgkmcnt(6)
	v_cvt_pk_bf16_f32 v26, v32, v30
	v_lshl_add_u64 v[48:49], v[46:47], 0, v[48:49]
	v_or_b32_e32 v30, s6, v61
	s_waitcnt lgkmcnt(4)
	v_cvt_pk_bf16_f32 v27, v34, v36
	s_waitcnt lgkmcnt(2)
	v_cvt_pk_bf16_f32 v28, v38, v40
	s_waitcnt lgkmcnt(0)
	v_cvt_pk_bf16_f32 v29, v42, v44
	global_store_dwordx4 v[48:49], v[26:29], off
	s_nop 1
	v_cvt_pk_bf16_f32 v26, v33, v31
	v_ashrrev_i32_e32 v31, 31, v30
	v_lshlrev_b64 v[30:31], 11, v[30:31]
	v_cvt_pk_bf16_f32 v27, v35, v37
	v_cvt_pk_bf16_f32 v28, v39, v41
	v_cvt_pk_bf16_f32 v29, v43, v45
	v_lshl_add_u64 v[30:31], v[46:47], 0, v[30:31]
	ds_read2_b32 v[32:33], v60 offset0:16 offset1:24
	ds_read2_b32 v[34:35], v60 offset0:49 offset1:57
	ds_read2_b32 v[36:37], v60 offset0:82 offset1:90
	ds_read2_b32 v[38:39], v60 offset0:115 offset1:123
	ds_read2_b32 v[40:41], v60 offset0:148 offset1:156
	ds_read2_b32 v[42:43], v60 offset0:181 offset1:189
	ds_read2_b32 v[44:45], v60 offset0:214 offset1:222
	ds_read2_b32 v[48:49], v60 offset0:247 offset1:255
	global_store_dwordx4 v[30:31], v[26:29], off
	v_or_b32_e32 v30, s6, v62
	v_ashrrev_i32_e32 v31, 31, v30
	v_lshlrev_b64 v[30:31], 11, v[30:31]
	v_lshl_add_u64 v[30:31], v[46:47], 0, v[30:31]
	s_waitcnt lgkmcnt(6)
	v_cvt_pk_bf16_f32 v26, v32, v34
	s_waitcnt lgkmcnt(4)
	v_cvt_pk_bf16_f32 v27, v36, v38
	s_waitcnt lgkmcnt(2)
	v_cvt_pk_bf16_f32 v28, v40, v42
	s_waitcnt lgkmcnt(0)
	v_cvt_pk_bf16_f32 v29, v44, v48
	global_store_dwordx4 v[30:31], v[26:29], off
	v_or_b32_e32 v30, s6, v63
	v_ashrrev_i32_e32 v31, 31, v30
	v_lshlrev_b64 v[30:31], 11, v[30:31]
	v_lshl_add_u64 v[30:31], v[46:47], 0, v[30:31]
	v_cvt_pk_bf16_f32 v26, v33, v35
	v_cvt_pk_bf16_f32 v27, v37, v39
	v_cvt_pk_bf16_f32 v28, v41, v43
	v_cvt_pk_bf16_f32 v29, v45, v49
	global_store_dwordx4 v[30:31], v[26:29], off
	s_waitcnt lgkmcnt(0)
	s_branch .LBB0_30
